# lru_m1: all four gate-weight tiles loaded at job top (prefetch regs) instead of one per MFMA stage
# baseline (speedup 1.0000x reference)
.LBB0_381:
	s_ashr_i32 s12, s94, 3
	s_and_b32 s15, s94, 7
	s_lshl_b32 s14, s12, 6
	s_cmp_lt_i32 s12, 64
	s_movk_i32 s0, 0xff00
	v_mov_b32_e32 v130, v180
	s_cselect_b32 s0, s0, 0x7ffff800
	v_readlane_b32 s60, v254, 12
	s_cselect_b32 s2, 0x100, s21
	s_and_b32 s10, s0, s14
	s_add_i32 s11, s14, -2
	s_lshl_b32 s16, s15, 7
	s_lshl_b32 s0, s15, 8
	v_readlane_b32 s66, v254, 18
	v_lshlrev_b32_e32 v134, 3, v130
	v_readlane_b32 s67, v254, 19
	s_add_u32 s0, s66, s0
	v_and_b32_e32 v86, 0x78, v134
	v_add_u32_e32 v85, 0x200, v130
	s_addc_u32 s1, s67, 0
	v_lshlrev_b32_e32 v112, 1, v86
	v_ashrrev_i32_e32 v0, 4, v85
	v_lshl_add_u64 v[62:63], s[0:1], 0, v[112:113]
	s_add_i32 s13, s10, s2
	v_add_u32_e32 v0, s11, v0
	s_movk_i32 s0, 0x230
	v_cmp_gt_i32_e64 s[8:9], s0, v130
	v_cmp_gt_i32_e64 s[0:1], s13, v0
	v_cmp_le_i32_e32 vcc, s10, v0
	s_and_b64 s[0:1], s[8:9], s[0:1]
	v_add_u32_e32 v84, 0x400, v130
	v_mov_b32_e32 v2, s14
	s_and_b64 s[0:1], s[0:1], vcc
	v_ashrrev_i32_e32 v3, 4, v84
	v_cndmask_b32_e64 v0, v2, v0, s[0:1]
	v_add_u32_e32 v3, s11, v3
	v_mad_i64_i32 v[0:1], s[2:3], v0, s77, v[62:63]
	v_cmp_gt_i32_e64 s[6:7], 48, v130
	v_cmp_gt_i32_e64 s[4:5], s13, v3
	v_cmp_le_i32_e32 vcc, s10, v3
	s_and_b64 s[2:3], s[6:7], s[4:5]
	s_and_b64 s[4:5], s[2:3], vcc
	v_readlane_b32 s64, v254, 16
	v_readlane_b32 s65, v254, 17
	v_readlane_b32 s68, v254, 20
	v_readlane_b32 s69, v254, 21
	v_readlane_b32 s70, v254, 22
	v_readlane_b32 s71, v254, 23
	v_readlane_b32 s72, v254, 24
	v_readlane_b32 s73, v254, 25
	v_readlane_b32 s74, v254, 26
	v_readlane_b32 s75, v254, 27
	v_cndmask_b32_e64 v2, v2, v3, s[4:5]
	v_mad_i64_i32 v[2:3], s[2:3], v2, s77, v[62:63]
	v_and_b32_e32 v131, 0x7f, v130
	v_readlane_b32 s64, v254, 44
	v_or_b32_e32 v133, s16, v131
	v_readlane_b32 s65, v254, 45
	v_readlane_b32 s66, v254, 46
	v_readlane_b32 s67, v254, 47
	v_readlane_b32 s76, v254, 56
	v_readlane_b32 s77, v254, 57
	global_load_dwordx4 v[56:59], v[0:1], off
	global_load_dwordx4 v[52:55], v[2:3], off
	v_lshlrev_b32_e32 v0, 2, v133
	v_mov_b32_e32 v1, v113
	v_readlane_b32 s78, v254, 58
	v_readlane_b32 s79, v254, 59
	s_mov_b64 s[64:65], s[76:77]
	v_lshl_add_u64 v[2:3], s[64:65], 0, v[0:1]
	s_movk_i32 s2, 0x2000
	v_add_co_u32_e32 v4, vcc, s2, v2
	s_movk_i32 s2, 0x3000
	s_nop 0
	v_addc_co_u32_e32 v5, vcc, 0, v3, vcc
	v_readlane_b32 s62, v254, 14
	v_ashrrev_i32_e32 v64, 4, v130
	v_add_co_u32_e32 v2, vcc, s2, v2
	s_lshl_b32 s2, s15, 15
	v_readlane_b32 s63, v254, 15
	v_lshl_or_b32 v24, v64, 7, v86
	s_add_u32 s2, s62, s2
	s_addc_u32 s3, s63, 0
	v_ashrrev_i32_e32 v25, 31, v24
	v_addc_co_u32_e32 v3, vcc, 0, v3, vcc
	v_lshrrev_b32_e32 v66, 1, v130
	v_lshl_add_u64 v[60:61], v[24:25], 1, s[2:3]
	s_mov_b64 s[66:67], s[78:79]
	global_load_dword v82, v[4:5], off offset:-4096
	global_load_dword v67, v[4:5], off
	global_load_dword v80, v[2:3], off
	global_load_dword v83, v0, s[64:65]
	global_load_dword v81, v0, s[66:67]
	v_and_b32_e32 v65, 0x60, v66
	v_lshrrev_b32_e32 v0, 2, v130
	v_add_co_u32_e32 v28, vcc, 0x2000, v60
	v_and_or_b32 v136, v0, 12, v65
	s_nop 0
	v_addc_co_u32_e32 v29, vcc, 0, v61, vcc
	v_or_b32_e32 v0, s16, v136
	v_add_co_u32_e32 v32, vcc, 0x4000, v60
	v_lshlrev_b32_e32 v0, 2, v0
	v_readlane_b32 s52, v254, 0
	v_addc_co_u32_e32 v33, vcc, 0, v61, vcc
	global_load_dwordx4 v[76:79], v0, s[18:19]
	global_load_dwordx4 v[68:71], v0, s[22:23]
	global_load_dwordx4 v[48:51], v0, s[18:19] offset:64
	global_load_dwordx4 v[40:43], v0, s[22:23] offset:64
	v_readlane_b32 s53, v254, 1
	v_or_b32_e32 v1, 0x1000, v0
	v_or_b32_e32 v4, 0x1040, v0
	v_add_co_u32_e32 v36, vcc, 0x6000, v60
	s_nop 1
	global_load_dwordx4 v[72:75], v0, s[52:53]
	global_load_dwordx4 v[44:47], v0, s[52:53] offset:64
	global_load_dwordx4 v[20:23], v1, s[18:19]
	global_load_dwordx4 v[12:15], v1, s[22:23]
	global_load_dwordx4 v[16:19], v1, s[52:53]
	global_load_dwordx4 v[8:11], v4, s[18:19]
	s_nop 0
	global_load_dwordx4 v[0:3], v4, s[22:23]
	s_nop 0
	global_load_dwordx4 v[4:7], v4, s[52:53]
	v_addc_co_u32_e32 v37, vcc, 0, v61, vcc
	global_load_dwordx4 v[24:27], v[60:61], off
	s_nop 0
	global_load_dwordx4 v[28:31], v[28:29], off
	s_nop 0
	global_load_dwordx4 v[32:35], v[32:33], off
	s_nop 0
	global_load_dwordx4 v[36:39], v[36:37], off
	v_add_co_u32_e32 v230, vcc, 0x40000, v60
	s_nop 1
	v_addc_co_u32_e32 v231, vcc, 0, v61, vcc
	global_load_dwordx4 v[182:185], v[230:231], off
	v_add_co_u32_e32 v230, vcc, 0x42000, v60
	s_nop 1
	v_addc_co_u32_e32 v231, vcc, 0, v61, vcc
	global_load_dwordx4 v[186:189], v[230:231], off
	v_add_co_u32_e32 v230, vcc, 0x44000, v60
	s_nop 1
	v_addc_co_u32_e32 v231, vcc, 0, v61, vcc
	global_load_dwordx4 v[190:193], v[230:231], off
	v_add_co_u32_e32 v230, vcc, 0x46000, v60
	s_nop 1
	v_addc_co_u32_e32 v231, vcc, 0, v61, vcc
	global_load_dwordx4 v[194:197], v[230:231], off
	v_add_co_u32_e32 v230, vcc, 0x80000, v60
	s_nop 1
	v_addc_co_u32_e32 v231, vcc, 0, v61, vcc
	global_load_dwordx4 v[198:201], v[230:231], off
	v_add_co_u32_e32 v230, vcc, 0x82000, v60
	s_nop 1
	v_addc_co_u32_e32 v231, vcc, 0, v61, vcc
	global_load_dwordx4 v[202:205], v[230:231], off
	v_add_co_u32_e32 v230, vcc, 0x84000, v60
	s_nop 1
	v_addc_co_u32_e32 v231, vcc, 0, v61, vcc
	global_load_dwordx4 v[206:209], v[230:231], off
	v_add_co_u32_e32 v230, vcc, 0x86000, v60
	s_nop 1
	v_addc_co_u32_e32 v231, vcc, 0, v61, vcc
	global_load_dwordx4 v[210:213], v[230:231], off
	v_add_co_u32_e32 v230, vcc, 0xc0000, v60
	s_nop 1
	v_addc_co_u32_e32 v231, vcc, 0, v61, vcc
	global_load_dwordx4 v[214:217], v[230:231], off
	v_add_co_u32_e32 v230, vcc, 0xc2000, v60
	s_nop 1
	v_addc_co_u32_e32 v231, vcc, 0, v61, vcc
	global_load_dwordx4 v[218:221], v[230:231], off
	v_add_co_u32_e32 v230, vcc, 0xc4000, v60
	s_nop 1
	v_addc_co_u32_e32 v231, vcc, 0, v61, vcc
	global_load_dwordx4 v[222:225], v[230:231], off
	v_add_co_u32_e32 v230, vcc, 0xc6000, v60
	s_nop 1
	v_addc_co_u32_e32 v231, vcc, 0, v61, vcc
	global_load_dwordx4 v[226:229], v[230:231], off
	s_movk_i32 s2, 0x430
	s_movk_i32 s77, 0x5040
	v_cmp_gt_i32_e32 vcc, s2, v130
	v_lshl_add_u32 v86, v86, 2, 0
	v_readlane_b32 s61, v254, 13
	v_readlane_b32 s68, v254, 48
	v_readlane_b32 s69, v254, 49
	v_readlane_b32 s70, v254, 50
	v_readlane_b32 s71, v254, 51
	v_readlane_b32 s72, v254, 52
	v_readlane_b32 s73, v254, 53
	v_readlane_b32 s74, v254, 54
	v_readlane_b32 s75, v254, 55
	v_readlane_b32 s54, v254, 2
	v_readlane_b32 s55, v254, 3
	v_readlane_b32 s56, v254, 4
	v_readlane_b32 s57, v254, 5
	v_readlane_b32 s58, v254, 6
	v_readlane_b32 s59, v254, 7
	s_and_saveexec_b64 s[2:3], vcc
	s_cbranch_execz .LBB0_383
	v_add_u32_e32 v87, s11, v64
	v_cmp_le_i32_e32 vcc, s10, v87
	v_cmp_gt_i32_e64 s[10:11], s13, v87
	v_mov_b32_e32 v88, s14
	s_and_b64 vcc, vcc, s[10:11]
	v_cndmask_b32_e32 v87, v88, v87, vcc
	v_mad_i64_i32 v[62:63], s[10:11], v87, s77, v[62:63]
	global_load_dwordx4 v[88:91], v[62:63], off
	v_and_b32_e32 v62, 0x3fffff80, v134
	v_lshl_add_u32 v63, v62, 2, v86
	v_cndmask_b32_e64 v62, 0, 1.0, vcc
	s_waitcnt vmcnt(0)
	v_lshlrev_b32_e32 v92, 16, v88
	v_and_b32_e32 v93, 0xffff0000, v88
	v_lshlrev_b32_e32 v94, 16, v89
	v_and_b32_e32 v95, 0xffff0000, v89
	v_lshlrev_b32_e32 v96, 16, v90
	v_and_b32_e32 v97, 0xffff0000, v90
	v_lshlrev_b32_e32 v98, 16, v91
	v_and_b32_e32 v99, 0xffff0000, v91
	v_pk_mul_f32 v[88:89], v[62:63], v[92:93] op_sel_hi:[0,1]
	v_pk_mul_f32 v[90:91], v[62:63], v[94:95] op_sel_hi:[0,1]
	v_pk_mul_f32 v[92:93], v[62:63], v[96:97] op_sel_hi:[0,1]
	v_pk_mul_f32 v[94:95], v[62:63], v[98:99] op_sel_hi:[0,1]
	ds_write_b128 v63, v[88:91]
	ds_write_b128 v63, v[92:95] offset:16

.LBB0_387:
	s_or_b64 exec, exec, s[0:1]
	s_waitcnt vmcnt(0)
	v_lshlrev_b32_e32 v52, 2, v131
	v_lshlrev_b32_e32 v53, 2, v130
	v_add_u32_e32 v114, 0, v52
	v_and_b32_e32 v53, 0xfffffe00, v53
	s_waitcnt lgkmcnt(0)
	s_barrier
	v_add_u32_e32 v55, v114, v53
	v_add3_u32 v53, 0, v53, v52
	ds_read2st64_b32 v[58:59], v53 offset0:2 offset1:4
	ds_read2st64_b32 v[56:57], v55 offset1:8
	v_ashrrev_i32_e32 v132, 7, v130
	s_movk_i32 s0, 0x204
	v_readlane_b32 s2, v253, 21
	s_waitcnt lgkmcnt(0)
	v_mul_f32_e32 v52, v82, v58
	v_fmac_f32_e32 v52, v83, v56
	v_fmac_f32_e32 v52, v67, v59
	ds_read2st64_b32 v[58:59], v53 offset0:6 offset1:10
	s_waitcnt lgkmcnt(0)
	v_mul_f32_e32 v54, v82, v59
	v_fmac_f32_e32 v54, v83, v57
	ds_read2st64_b32 v[56:57], v53 offset0:12 offset1:14
	v_fmac_f32_e32 v52, v80, v58
	v_add_f32_e32 v52, v81, v52
	s_waitcnt lgkmcnt(0)
	v_fmac_f32_e32 v54, v67, v56
	v_fmac_f32_e32 v54, v80, v57
	ds_read2st64_b32 v[56:57], v55 offset0:16 offset1:24
	ds_read2st64_b32 v[58:59], v53 offset0:18 offset1:20
	v_add_f32_e32 v54, v81, v54
	s_waitcnt lgkmcnt(0)
	v_mul_f32_e32 v62, v82, v58
	v_fmac_f32_e32 v62, v83, v56
	v_fmac_f32_e32 v62, v67, v59
	ds_read2st64_b32 v[58:59], v53 offset0:22 offset1:26
	s_waitcnt lgkmcnt(0)
	v_fmac_f32_e32 v62, v80, v58
	v_add_f32_e32 v56, v81, v62
	v_mul_f32_e32 v62, v82, v59
	ds_read2st64_b32 v[58:59], v53 offset0:28 offset1:30
	v_fmac_f32_e32 v62, v83, v57
	s_waitcnt lgkmcnt(0)
	v_fmac_f32_e32 v62, v67, v58
	v_fmac_f32_e32 v62, v80, v59
	v_add_f32_e32 v57, v81, v62
	ds_read2st64_b32 v[58:59], v55 offset0:32 offset1:40
	ds_read2st64_b32 v[62:63], v53 offset0:34 offset1:36
	s_waitcnt lgkmcnt(0)
	v_mul_f32_e32 v84, v82, v62
	v_fmac_f32_e32 v84, v83, v58
	v_fmac_f32_e32 v84, v67, v63
	ds_read2st64_b32 v[62:63], v53 offset0:38 offset1:42
	s_waitcnt lgkmcnt(0)
	v_fmac_f32_e32 v84, v80, v62
	v_add_f32_e32 v58, v81, v84
	v_mul_f32_e32 v84, v82, v63
	ds_read2st64_b32 v[62:63], v53 offset0:44 offset1:46
	v_fmac_f32_e32 v84, v83, v59
	s_waitcnt lgkmcnt(0)
	v_fmac_f32_e32 v84, v67, v62
	v_fmac_f32_e32 v84, v80, v63
	v_add_f32_e32 v59, v81, v84
	ds_read2st64_b32 v[62:63], v55 offset0:48 offset1:56
	ds_read2st64_b32 v[84:85], v53 offset0:50 offset1:52
	s_waitcnt lgkmcnt(0)
	v_mul_f32_e32 v86, v82, v84
	v_fmac_f32_e32 v86, v83, v62
	v_fmac_f32_e32 v86, v67, v85
	ds_read2st64_b32 v[84:85], v53 offset0:54 offset1:58
	s_waitcnt lgkmcnt(0)
	v_fmac_f32_e32 v86, v80, v84
	v_mul_f32_e32 v84, v82, v85
	v_fmac_f32_e32 v84, v83, v63
	ds_read2st64_b32 v[62:63], v53 offset0:60 offset1:62
	v_add_f32_e32 v86, v81, v86
	s_waitcnt lgkmcnt(0)
	v_fmac_f32_e32 v84, v67, v62
	v_fmac_f32_e32 v84, v80, v63
	v_add_f32_e32 v87, v81, v84
	ds_read2st64_b32 v[62:63], v55 offset0:64 offset1:72
	ds_read2st64_b32 v[84:85], v53 offset0:66 offset1:68
	s_waitcnt lgkmcnt(0)
	v_mul_f32_e32 v88, v82, v84
	v_fmac_f32_e32 v88, v83, v62
	v_fmac_f32_e32 v88, v67, v85
	ds_read2st64_b32 v[84:85], v53 offset0:70 offset1:74
	s_waitcnt lgkmcnt(0)
	v_fmac_f32_e32 v88, v80, v84
	v_mul_f32_e32 v84, v82, v85
	v_fmac_f32_e32 v84, v83, v63
	ds_read2st64_b32 v[62:63], v53 offset0:76 offset1:78
	v_add_f32_e32 v88, v81, v88
	s_waitcnt lgkmcnt(0)
	v_fmac_f32_e32 v84, v67, v62
	v_fmac_f32_e32 v84, v80, v63
	v_add_f32_e32 v89, v81, v84
	ds_read2st64_b32 v[62:63], v55 offset0:80 offset1:88
	ds_read2st64_b32 v[84:85], v53 offset0:82 offset1:84
	s_waitcnt lgkmcnt(0)
	v_mul_f32_e32 v90, v82, v84
	v_fmac_f32_e32 v90, v83, v62
	v_fmac_f32_e32 v90, v67, v85
	ds_read2st64_b32 v[84:85], v53 offset0:86 offset1:90
	s_waitcnt lgkmcnt(0)
	v_fmac_f32_e32 v90, v80, v84
	v_mul_f32_e32 v84, v82, v85
	v_fmac_f32_e32 v84, v83, v63
	ds_read2st64_b32 v[62:63], v53 offset0:92 offset1:94
	v_add_f32_e32 v90, v81, v90
	s_waitcnt lgkmcnt(0)
	v_fmac_f32_e32 v84, v67, v62
	v_fmac_f32_e32 v84, v80, v63
	v_add_f32_e32 v91, v81, v84
	ds_read2st64_b32 v[62:63], v55 offset0:96 offset1:104
	ds_read2st64_b32 v[84:85], v53 offset0:98 offset1:100
	s_waitcnt lgkmcnt(0)
	v_mul_f32_e32 v92, v82, v84
	v_fmac_f32_e32 v92, v83, v62
	v_fmac_f32_e32 v92, v67, v85
	ds_read2st64_b32 v[84:85], v53 offset0:102 offset1:106
	s_waitcnt lgkmcnt(0)
	v_fmac_f32_e32 v92, v80, v84
	v_mul_f32_e32 v84, v82, v85
	v_fmac_f32_e32 v84, v83, v63
	ds_read2st64_b32 v[62:63], v53 offset0:108 offset1:110
	v_add_f32_e32 v92, v81, v92
	s_waitcnt lgkmcnt(0)
	v_fmac_f32_e32 v84, v67, v62
	v_fmac_f32_e32 v84, v80, v63
	v_add_f32_e32 v93, v81, v84
	ds_read2st64_b32 v[62:63], v55 offset0:112 offset1:120
	ds_read2st64_b32 v[84:85], v53 offset0:114 offset1:116
	s_waitcnt lgkmcnt(0)
	v_mul_f32_e32 v55, v82, v84
	v_fmac_f32_e32 v55, v83, v62
	v_fmac_f32_e32 v55, v67, v85
	ds_read2st64_b32 v[84:85], v53 offset0:118 offset1:122
	s_waitcnt lgkmcnt(0)
	v_mul_f32_e32 v82, v82, v85
	v_fmac_f32_e32 v82, v83, v63
	ds_read2st64_b32 v[62:63], v53 offset0:124 offset1:126
	v_fmac_f32_e32 v55, v80, v84
	v_add_f32_e32 v55, v81, v55
	s_waitcnt lgkmcnt(0)
	v_fmac_f32_e32 v82, v67, v62
	v_fmac_f32_e32 v82, v80, v63
	v_mad_u64_u32 v[62:63], s[0:1], v132, s0, v[114:115]
	s_movk_i32 s1, 0x110
	v_lshlrev_b32_e32 v67, 1, v131
	v_mul_lo_u32 v63, v132, s1
	ds_write_b32 v62, v52 offset:34304
	v_cvt_pk_bf16_f32 v52, v52, v113
	v_add3_u32 v63, s33, v67, v63
	ds_write_b16 v63, v52
	ds_write_b32 v62, v54 offset:36368
	v_cvt_pk_bf16_f32 v52, v54, v113
	ds_write_b16 v63, v52 offset:1088
	ds_write_b32 v62, v56 offset:38432
	v_cvt_pk_bf16_f32 v52, v56, v113
	ds_write_b16 v63, v52 offset:2176
	ds_write_b32 v62, v57 offset:40496
	v_cvt_pk_bf16_f32 v52, v57, v113
	ds_write_b16 v63, v52 offset:3264
	ds_write_b32 v62, v58 offset:42560
	v_cvt_pk_bf16_f32 v52, v58, v113
	ds_write_b16 v63, v52 offset:4352
	ds_write_b32 v62, v59 offset:44624
	v_cvt_pk_bf16_f32 v52, v59, v113
	ds_write_b16 v63, v52 offset:5440
	ds_write_b32 v62, v86 offset:46688
	v_cvt_pk_bf16_f32 v52, v86, v113
	ds_write_b16 v63, v52 offset:6528
	ds_write_b32 v62, v87 offset:48752
	v_cvt_pk_bf16_f32 v52, v87, v113
	ds_write_b16 v63, v52 offset:7616
	ds_write_b32 v62, v88 offset:50816
	v_cvt_pk_bf16_f32 v52, v88, v113
	ds_write_b16 v63, v52 offset:8704
	ds_write_b32 v62, v89 offset:52880
	v_cvt_pk_bf16_f32 v52, v89, v113
	ds_write_b16 v63, v52 offset:9792
	ds_write_b32 v62, v90 offset:54944
	v_cvt_pk_bf16_f32 v52, v90, v113
	ds_write_b16 v63, v52 offset:10880
	ds_write_b32 v62, v91 offset:57008
	v_cvt_pk_bf16_f32 v52, v91, v113
	ds_write_b16 v63, v52 offset:11968
	ds_write_b32 v62, v92 offset:59072
	v_cvt_pk_bf16_f32 v52, v92, v113
	ds_write_b16 v63, v52 offset:13056
	ds_write_b32 v62, v93 offset:61136
	v_cvt_pk_bf16_f32 v52, v93, v113
	ds_write_b16 v63, v52 offset:14144
	ds_write_b32 v62, v55 offset:63200
	v_cvt_pk_bf16_f32 v52, v55, v113
	v_add_f32_e32 v53, v81, v82
	ds_write_b16 v63, v52 offset:15232
	ds_write_b32 v62, v53 offset:65264
	v_cvt_pk_bf16_f32 v52, v53, v113
	ds_write_b16 v63, v52 offset:16320
	v_mul_lo_u32 v52, v64, s1
	v_add3_u32 v62, s2, v112, v52
	v_ashrrev_i32_e32 v52, 3, v130
	v_and_b32_e32 v53, 15, v130
	s_movk_i32 s0, 0xffe0
	v_and_or_b32 v112, v52, s0, v53
	s_mov_b32 s0, 0x40000
	ds_write_b128 v62, v[24:27]
	ds_write_b128 v62, v[28:31] offset:8704
	ds_write_b128 v62, v[32:35] offset:17408
	ds_write_b128 v62, v[36:39] offset:26112
	v_add_co_u32_e32 v24, vcc, s0, v60
	s_mov_b32 s0, 0x42000
	s_nop 0
	v_addc_co_u32_e32 v25, vcc, 0, v61, vcc
	v_add_co_u32_e32 v28, vcc, s0, v60
	s_mov_b32 s0, 0x44000
	s_nop 0
	v_addc_co_u32_e32 v29, vcc, 0, v61, vcc
	v_add_co_u32_e32 v32, vcc, s0, v60
	s_nop 0
	s_nop 0
	v_addc_co_u32_e32 v33, vcc, 0, v61, vcc
	s_mov_b32 s0, 0x46000
	s_nop 0
	v_and_b32_e32 v52, 24, v66
	s_nop 0
	v_add_co_u32_e32 v32, vcc, s0, v60
	v_lshlrev_b32_e32 v56, 1, v52
	s_nop 0
	v_addc_co_u32_e32 v33, vcc, 0, v61, vcc
	v_or_b32_e32 v57, v65, v53
	s_nop 0
	v_mul_lo_u32 v32, v112, s1
	s_waitcnt lgkmcnt(0)
	s_barrier
	v_add3_u32 v32, s33, v56, v32
	v_mul_u32_u24_e32 v33, 0x110, v57
	v_add3_u32 v33, s2, v56, v33
	ds_read_b128 v[56:59], v32
	ds_read_b128 v[64:67], v33
	ds_read_b128 v[84:87], v32 offset:64
	ds_read_b128 v[88:91], v33 offset:64
	s_waitcnt lgkmcnt(2)
	v_mfma_f32_16x16x32_bf16 v[80:83], v[64:67], v[56:59], 0
	ds_read_b128 v[92:95], v32 offset:128
	ds_read_b128 v[96:99], v33 offset:128
	ds_read_b128 v[104:107], v32 offset:192
	ds_read_b128 v[108:111], v33 offset:192
	ds_read_b128 v[138:141], v33 offset:4416
	s_waitcnt lgkmcnt(5)
	v_mfma_f32_16x16x32_bf16 v[80:83], v[88:91], v[84:87], v[80:83]
	ds_read_b128 v[142:145], v33 offset:4480
	s_mov_b32 s0, 0x80000
	ds_read_b128 v[146:149], v32 offset:4544
	s_waitcnt lgkmcnt(5)
	v_mfma_f32_16x16x32_bf16 v[80:83], v[96:99], v[92:95], v[80:83]
	s_waitcnt lgkmcnt(3)
	v_mfma_f32_16x16x32_bf16 v[100:103], v[108:111], v[104:107], v[80:83]
	s_nop 5
	ds_read_b128 v[80:83], v33 offset:4352
	s_waitcnt lgkmcnt(0)
	v_mfma_f32_16x16x32_bf16 v[56:59], v[80:83], v[56:59], 0
	v_add_f32_e32 v100, v76, v100
	v_mul_f32_e32 v100, 0xbfb8aa3b, v100
	v_exp_f32_e32 v100, v100
	v_mfma_f32_16x16x32_bf16 v[56:59], v[138:141], v[84:87], v[56:59]
	v_add_f32_e32 v100, 1.0, v100
	v_mfma_f32_16x16x32_bf16 v[56:59], v[142:145], v[92:95], v[56:59]
	ds_read_b128 v[92:95], v33 offset:4544
	v_rcp_f32_e32 v100, v100
	s_waitcnt lgkmcnt(0)
	v_mfma_f32_16x16x32_bf16 v[84:87], v[92:95], v[104:107], v[56:59]
	s_nop 3
	ds_read_b128 v[56:59], v32 offset:4352
	ds_read_b128 v[104:107], v32 offset:4416
	v_mul_f32_e32 v100, v72, v100
	s_waitcnt lgkmcnt(1)
	v_mfma_f32_16x16x32_bf16 v[64:67], v[64:67], v[56:59], 0
	v_add_f32_e32 v135, v100, v100
	s_waitcnt lgkmcnt(0)
	v_mfma_f32_16x16x32_bf16 v[64:67], v[88:91], v[104:107], v[64:67]
	ds_read_b128 v[88:91], v32 offset:4480
	s_waitcnt lgkmcnt(0)
	s_barrier
	s_nop 0
	ds_write_b128 v62, v[182:185]
	s_nop 0
	ds_write_b128 v62, v[186:189] offset:8704
	s_nop 0
	ds_write_b128 v62, v[190:193] offset:17408
	s_nop 0
	ds_write_b128 v62, v[194:197] offset:26112
	v_add_co_u32_e32 v24, vcc, s0, v60
	s_mov_b32 s0, 0x82000
	s_nop 0
	v_addc_co_u32_e32 v25, vcc, 0, v61, vcc
	v_add_co_u32_e32 v28, vcc, s0, v60
	s_mov_b32 s0, 0x84000
	s_nop 0
	v_addc_co_u32_e32 v29, vcc, 0, v61, vcc
	v_add_co_u32_e32 v34, vcc, s0, v60
	s_nop 0
	s_nop 0
	v_addc_co_u32_e32 v35, vcc, 0, v61, vcc
	s_mov_b32 s0, 0x86000
	s_nop 0
	v_add_co_u32_e32 v38, vcc, s0, v60
	s_nop 0
	s_nop 0
	v_addc_co_u32_e32 v39, vcc, 0, v61, vcc
	s_nop 0
	v_mfma_f32_16x16x32_bf16 v[56:59], v[80:83], v[56:59], 0
	s_waitcnt lgkmcnt(0)
	s_barrier
	s_mov_b32 s0, 0xc0000
	v_mfma_f32_16x16x32_bf16 v[56:59], v[138:141], v[104:107], v[56:59]
	s_waitcnt lgkmcnt(4)
	v_mfma_f32_16x16x32_bf16 v[64:67], v[96:99], v[88:91], v[64:67]
	v_mfma_f32_16x16x32_bf16 v[56:59], v[142:145], v[88:91], v[56:59]
	v_mfma_f32_16x16x32_bf16 v[96:99], v[108:111], v[146:149], v[64:67]
	v_mfma_f32_16x16x32_bf16 v[80:83], v[92:95], v[146:149], v[56:59]
	s_nop 5
	ds_read_b128 v[56:59], v32
	ds_read_b128 v[64:67], v33
	ds_read_b128 v[92:95], v32 offset:64
	ds_read_b128 v[104:107], v33 offset:64
	ds_read_b128 v[138:141], v32 offset:128
	ds_read_b128 v[142:145], v33 offset:128
	s_waitcnt lgkmcnt(4)
	v_mfma_f32_16x16x32_bf16 v[88:91], v[64:67], v[56:59], 0
	ds_read_b128 v[146:149], v32 offset:192
	ds_read_b128 v[150:153], v33 offset:192
	ds_read_b128 v[154:157], v33 offset:4416
	ds_read_b128 v[158:161], v33 offset:4480
	s_waitcnt lgkmcnt(6)
	v_mfma_f32_16x16x32_bf16 v[88:91], v[104:107], v[92:95], v[88:91]
	ds_read_b128 v[162:165], v32 offset:4480
	s_waitcnt lgkmcnt(5)
	v_mfma_f32_16x16x32_bf16 v[88:91], v[142:145], v[138:141], v[88:91]
	s_waitcnt lgkmcnt(3)
	v_mfma_f32_16x16x32_bf16 v[108:111], v[150:153], v[146:149], v[88:91]
	s_nop 5
	ds_read_b128 v[88:91], v33 offset:4352
	s_waitcnt lgkmcnt(0)
	v_mfma_f32_16x16x32_bf16 v[56:59], v[88:91], v[56:59], 0
	v_mfma_f32_16x16x32_bf16 v[56:59], v[154:157], v[92:95], v[56:59]
	v_mfma_f32_16x16x32_bf16 v[56:59], v[158:161], v[138:141], v[56:59]
	ds_read_b128 v[138:141], v33 offset:4544
	s_waitcnt lgkmcnt(0)
	v_mfma_f32_16x16x32_bf16 v[92:95], v[138:141], v[146:149], v[56:59]
	s_nop 4
	ds_read_b128 v[56:59], v32 offset:4352
	ds_read_b128 v[146:149], v32 offset:4416
	s_waitcnt lgkmcnt(1)
	v_mfma_f32_16x16x32_bf16 v[64:67], v[64:67], v[56:59], 0
	v_mfma_f32_16x16x32_bf16 v[56:59], v[88:91], v[56:59], 0
	s_waitcnt lgkmcnt(0)
	v_mfma_f32_16x16x32_bf16 v[64:67], v[104:107], v[146:149], v[64:67]
	v_mfma_f32_16x16x32_bf16 v[56:59], v[154:157], v[146:149], v[56:59]
	v_mfma_f32_16x16x32_bf16 v[64:67], v[142:145], v[162:165], v[64:67]
	ds_read_b128 v[142:145], v32 offset:4544
	s_waitcnt lgkmcnt(0)
	s_barrier
	s_nop 0
	ds_write_b128 v62, v[198:201]
	s_nop 0
	ds_write_b128 v62, v[202:205] offset:8704
	s_nop 0
	ds_write_b128 v62, v[206:209] offset:17408
	s_nop 0
	ds_write_b128 v62, v[210:213] offset:26112
	v_add_co_u32_e32 v24, vcc, s0, v60
	s_mov_b32 s0, 0xc2000
	s_nop 0
	v_addc_co_u32_e32 v25, vcc, 0, v61, vcc
	v_mfma_f32_16x16x32_bf16 v[56:59], v[158:161], v[162:165], v[56:59]
	s_nop 0
	v_add_co_u32_e32 v24, vcc, s0, v60
	s_mov_b32 s0, 0xc4000
	s_nop 0
	v_addc_co_u32_e32 v25, vcc, 0, v61, vcc
	s_waitcnt lgkmcnt(4)
	v_mfma_f32_16x16x32_bf16 v[104:107], v[150:153], v[142:145], v[64:67]
	s_nop 2
	s_nop 0
	v_add_co_u32_e32 v24, vcc, s0, v60
	s_mov_b32 s0, 0xc6000
	s_nop 0
	v_addc_co_u32_e32 v25, vcc, 0, v61, vcc
	v_mfma_f32_16x16x32_bf16 v[88:91], v[138:141], v[142:145], v[56:59]
	s_nop 0
	v_add_co_u32_e32 v24, vcc, s0, v60
	s_nop 1
	v_addc_co_u32_e32 v25, vcc, 0, v61, vcc
	s_nop 0
	s_waitcnt lgkmcnt(0)
	s_barrier
	ds_read_b128 v[24:27], v32
	ds_read_b128 v[56:59], v33
	ds_read_b128 v[146:149], v32 offset:64
	ds_read_b128 v[150:153], v33 offset:64
	ds_read_b128 v[154:157], v32 offset:128
	ds_read_b128 v[158:161], v33 offset:128
	ds_read_b128 v[162:165], v32 offset:192
	ds_read_b128 v[166:169], v33 offset:192
	ds_read_b128 v[170:173], v33 offset:4352
	ds_read_b128 v[174:177], v33 offset:4416
	s_waitcnt lgkmcnt(8)
	v_mfma_f32_16x16x32_bf16 v[28:31], v[56:59], v[24:27], 0
	v_cmp_nlt_f32_e32 vcc, s10, v135
	s_waitcnt lgkmcnt(1)
	v_mfma_f32_16x16x32_bf16 v[24:27], v[170:173], v[24:27], 0
	v_mfma_f32_16x16x32_bf16 v[28:31], v[150:153], v[146:149], v[28:31]
	s_waitcnt lgkmcnt(0)
	v_mfma_f32_16x16x32_bf16 v[24:27], v[174:177], v[146:149], v[24:27]
	ds_read_b128 v[146:149], v33 offset:4480
	v_mfma_f32_16x16x32_bf16 v[28:31], v[158:161], v[154:157], v[28:31]
	s_waitcnt lgkmcnt(0)
	v_mfma_f32_16x16x32_bf16 v[24:27], v[146:149], v[154:157], v[24:27]
	ds_read_b128 v[154:157], v33 offset:4544
	v_mfma_f32_16x16x32_bf16 v[52:55], v[166:169], v[162:165], v[28:31]
	s_waitcnt lgkmcnt(0)
	v_mfma_f32_16x16x32_bf16 v[28:31], v[154:157], v[162:165], v[24:27]
	ds_read_b128 v[162:165], v32 offset:4416
	s_nop 2
	ds_read_b128 v[24:27], v32 offset:4352
	s_waitcnt lgkmcnt(0)
	v_mfma_f32_16x16x32_bf16 v[56:59], v[56:59], v[24:27], 0
	v_mfma_f32_16x16x32_bf16 v[24:27], v[170:173], v[24:27], 0
	v_mfma_f32_16x16x32_bf16 v[56:59], v[150:153], v[162:165], v[56:59]
	ds_read_b128 v[150:153], v32 offset:4480
	v_mfma_f32_16x16x32_bf16 v[24:27], v[174:177], v[162:165], v[24:27]
	s_waitcnt lgkmcnt(0)
	v_mfma_f32_16x16x32_bf16 v[56:59], v[158:161], v[150:153], v[56:59]
	ds_read_b128 v[158:161], v32 offset:4544
	s_waitcnt lgkmcnt(0)
	s_barrier
	s_nop 0
	ds_write_b128 v62, v[214:217]
	s_nop 0
	ds_write_b128 v62, v[218:221] offset:8704
	s_nop 0
	ds_write_b128 v62, v[222:225] offset:17408
	s_nop 0
	ds_write_b128 v62, v[226:229] offset:26112
	v_mfma_f32_16x16x32_bf16 v[24:27], v[146:149], v[150:153], v[24:27]
	s_waitcnt lgkmcnt(0)
	s_barrier
	ds_read_b128 v[34:37], v32
	ds_read_b128 v[64:67], v33
	ds_read_b128 v[138:141], v32 offset:64
	ds_read_b128 v[142:145], v33 offset:64
	s_waitcnt lgkmcnt(8)
	v_mfma_f32_16x16x32_bf16 v[56:59], v[166:169], v[158:161], v[56:59]
	ds_read_b128 v[146:149], v32 offset:128
	ds_read_b128 v[150:153], v33 offset:128
	v_mfma_f32_16x16x32_bf16 v[24:27], v[154:157], v[158:161], v[24:27]
	ds_read_b128 v[154:157], v32 offset:192
	ds_read_b128 v[158:161], v33 offset:192
	ds_read_b128 v[162:165], v33 offset:4352
	ds_read_b128 v[166:169], v33 offset:4416
	s_waitcnt lgkmcnt(8)
	v_mfma_f32_16x16x32_bf16 v[60:63], v[64:67], v[34:37], 0
	ds_read_b128 v[170:173], v32 offset:4416
	s_waitcnt lgkmcnt(2)
	v_mfma_f32_16x16x32_bf16 v[34:37], v[162:165], v[34:37], 0
	v_mfma_f32_16x16x32_bf16 v[60:63], v[142:145], v[138:141], v[60:63]
	s_waitcnt lgkmcnt(1)
	v_mfma_f32_16x16x32_bf16 v[34:37], v[166:169], v[138:141], v[34:37]
	ds_read_b128 v[138:141], v33 offset:4480
	v_mfma_f32_16x16x32_bf16 v[60:63], v[150:153], v[146:149], v[60:63]
	s_waitcnt lgkmcnt(0)
	v_mfma_f32_16x16x32_bf16 v[34:37], v[138:141], v[146:149], v[34:37]
	ds_read_b128 v[146:149], v33 offset:4544
	v_mfma_f32_16x16x32_bf16 v[60:63], v[158:161], v[154:157], v[60:63]
	s_waitcnt lgkmcnt(0)
	v_mfma_f32_16x16x32_bf16 v[36:39], v[146:149], v[154:157], v[34:37]
	ds_read_b128 v[154:157], v32 offset:4352
	s_waitcnt lgkmcnt(0)
	v_mfma_f32_16x16x32_bf16 v[64:67], v[64:67], v[154:157], 0
	v_mfma_f32_16x16x32_bf16 v[64:67], v[142:145], v[170:173], v[64:67]
	ds_read_b128 v[142:145], v32 offset:4480
	ds_read_b128 v[32:35], v32 offset:4544
	s_waitcnt lgkmcnt(0)
	s_barrier
	s_waitcnt lgkmcnt(1)
	v_mfma_f32_16x16x32_bf16 v[64:67], v[150:153], v[142:145], v[64:67]
	v_mfma_f32_16x16x32_bf16 v[150:153], v[162:165], v[154:157], 0
	v_mfma_f32_16x16x32_bf16 v[150:153], v[166:169], v[170:173], v[150:153]
	v_mfma_f32_16x16x32_bf16 v[138:141], v[138:141], v[142:145], v[150:153]
	s_waitcnt lgkmcnt(0)
	v_mfma_f32_16x16x32_bf16 v[64:67], v[158:161], v[32:35], v[64:67]
	v_mfma_f32_16x16x32_bf16 v[32:35], v[146:149], v[32:35], v[138:141]
	s_and_saveexec_b64 s[0:1], vcc
	s_xor_b64 s[0:1], exec, s[0:1]
	v_mul_f32_e32 v135, 0x3fb8aa3b, v135
	v_exp_f32_e32 v135, v135
	s_nop 0
	v_sub_f32_e32 v137, 1.0, v135
	s_andn2_saveexec_b64 s[0:1], s[0:1]
	v_fmamk_f32 v137, v135, 0x3d2aaaab, v116
	v_fma_f32 v137, v135, v137, 0.5
	v_fma_f32 v137, v135, v137, 1.0
	v_mul_f32_e64 v137, v137, -v135
	s_or_b64 exec, exec, s[0:1]
	v_add_f32_e32 v76, v76, v96
	v_add_f32_e32 v108, v68, v108
	v_mul_f32_e32 v76, 0xbfb8aa3b, v76
	v_mul_f32_e32 v108, 0xbfb8aa3b, v108
	v_exp_f32_e32 v76, v76
	v_exp_f32_e32 v108, v108
	v_mul_f32_e32 v100, 0x3fb8aa3b, v100
	v_exp_f32_e32 v138, v100
	v_lshl_add_u32 v100, v112, 7, v112
	v_add_u32_e32 v112, v100, v136
	v_lshl_add_u32 v135, v112, 2, 0
	v_add_f32_e32 v76, 1.0, v76
	v_add_f32_e32 v108, 1.0, v108
	v_sqrt_f32_e32 v112, v137
	ds_read_b32 v137, v135 offset:34304
	v_rcp_f32_e32 v76, v76
	v_rcp_f32_e32 v108, v108
	ds_write_b32 v135, v138
	v_add_u32_e32 v138, 0x10700, v135
	v_mul_f32_e32 v76, v72, v76
	s_waitcnt lgkmcnt(1)
	v_mul_f32_e32 v108, v108, v137
	v_add_f32_e32 v96, v76, v76
	v_mul_f32_e32 v108, v112, v108
	v_cmp_nlt_f32_e32 vcc, s10, v96
	ds_write_b32 v138, v108
	s_and_saveexec_b64 s[0:1], vcc
	s_xor_b64 s[0:1], exec, s[0:1]
	v_mul_f32_e32 v72, 0x3fb8aa3b, v96
	v_exp_f32_e32 v72, v72
	s_nop 0
	v_sub_f32_e32 v72, 1.0, v72
	s_andn2_saveexec_b64 s[0:1], s[0:1]
	v_fmamk_f32 v72, v96, 0x3d2aaaab, v116
	v_fma_f32 v72, v96, v72, 0.5
	v_fma_f32 v72, v96, v72, 1.0
	v_mul_f32_e64 v72, v72, -v96
	s_or_b64 exec, exec, s[0:1]
	v_add_f32_e32 v68, v68, v104
	v_mul_f32_e32 v68, 0xbfb8aa3b, v68
	v_exp_f32_e32 v68, v68
	v_sqrt_f32_e32 v72, v72
	v_add_f32_e32 v68, 1.0, v68
	v_rcp_f32_e32 v96, v68
	v_mul_f32_e32 v68, 0x3fb8aa3b, v76
	v_exp_f32_e32 v76, v68
	v_add_u32_e32 v68, 0x810, v100
	v_add_u32_e32 v104, v68, v136
	v_lshl_add_u32 v137, v104, 2, 0
	ds_write_b32 v137, v76
	ds_read_b32 v76, v137 offset:34304
	v_add_u32_e32 v139, 0x10700, v137
	s_waitcnt lgkmcnt(0)
	v_mul_f32_e32 v76, v96, v76
	v_mul_f32_e32 v72, v72, v76
	ds_write_b32 v139, v72
	v_add_f32_e32 v72, v77, v101
	v_mul_f32_e32 v72, 0xbfb8aa3b, v72
	v_exp_f32_e32 v72, v72
	s_nop 0
	v_add_f32_e32 v72, 1.0, v72
	v_rcp_f32_e32 v72, v72
	s_nop 0
	v_mul_f32_e32 v96, v73, v72
	v_add_f32_e32 v72, v96, v96
	v_cmp_nlt_f32_e32 vcc, s10, v72
	s_and_saveexec_b64 s[0:1], vcc
	s_xor_b64 s[0:1], exec, s[0:1]
	v_mul_f32_e32 v72, 0x3fb8aa3b, v72
	v_exp_f32_e32 v72, v72
	s_nop 0
	v_sub_f32_e32 v76, 1.0, v72
	s_andn2_saveexec_b64 s[0:1], s[0:1]
	v_fmamk_f32 v76, v72, 0x3d2aaaab, v116
	v_fma_f32 v76, v72, v76, 0.5
	v_fma_f32 v76, v72, v76, 1.0
	v_mul_f32_e64 v76, v76, -v72
	s_or_b64 exec, exec, s[0:1]
	v_add_f32_e32 v101, v69, v109
	v_mul_f32_e32 v101, 0xbfb8aa3b, v101
	v_mul_f32_e32 v96, 0x3fb8aa3b, v96
	v_exp_f32_e32 v101, v101
	v_exp_f32_e32 v96, v96
	v_sqrt_f32_e32 v76, v76
	v_or_b32_e32 v72, 1, v136
	v_add_f32_e32 v101, 1.0, v101
	ds_write_b32 v135, v96 offset:4
	ds_read_b32 v96, v135 offset:34308
	v_rcp_f32_e32 v101, v101
	v_add_u32_e32 v104, v72, v100
	s_waitcnt lgkmcnt(0)
	v_mul_f32_e32 v96, v101, v96
	v_mul_f32_e32 v76, v76, v96
	v_lshl_add_u32 v96, v104, 2, 0
	v_add_u32_e32 v140, 0x10700, v96
	ds_write_b32 v140, v76
	v_add_f32_e32 v76, v77, v97
	v_mul_f32_e32 v76, 0xbfb8aa3b, v76
	v_exp_f32_e32 v76, v76
	s_nop 0
	v_add_f32_e32 v76, 1.0, v76
	v_rcp_f32_e32 v76, v76
	s_nop 0
	v_mul_f32_e32 v73, v73, v76
	v_add_f32_e32 v77, v73, v73
	v_cmp_nlt_f32_e32 vcc, s10, v77
	s_and_saveexec_b64 s[0:1], vcc
	s_xor_b64 s[0:1], exec, s[0:1]
	v_mul_f32_e32 v76, 0x3fb8aa3b, v77
	v_exp_f32_e32 v76, v76
	s_nop 0
	v_sub_f32_e32 v76, 1.0, v76
	s_andn2_saveexec_b64 s[0:1], s[0:1]
	v_fmamk_f32 v76, v77, 0x3d2aaaab, v116
	v_fma_f32 v76, v77, v76, 0.5
	v_fma_f32 v76, v77, v76, 1.0
	v_mul_f32_e64 v76, v76, -v77
	s_or_b64 exec, exec, s[0:1]
	v_add_f32_e32 v69, v69, v105
	v_mul_f32_e32 v69, 0xbfb8aa3b, v69
	v_add_f32_e32 v96, v78, v102
	v_exp_f32_e32 v69, v69
	v_mul_f32_e32 v73, 0x3fb8aa3b, v73
	v_mul_f32_e32 v96, 0xbfb8aa3b, v96
	v_exp_f32_e32 v73, v73
	v_exp_f32_e32 v96, v96
	v_add_f32_e32 v69, 1.0, v69
	ds_read_b32 v77, v137 offset:34308
	v_rcp_f32_e32 v69, v69
	ds_write_b32 v137, v73 offset:4
	v_add_f32_e32 v73, 1.0, v96
	v_sqrt_f32_e32 v76, v76
	v_rcp_f32_e32 v73, v73
	v_add_u32_e32 v72, v68, v72
	s_waitcnt lgkmcnt(1)
	v_mul_f32_e32 v69, v69, v77
	v_lshl_add_u32 v72, v72, 2, 0
	v_mul_f32_e32 v69, v76, v69
	v_add_u32_e32 v141, 0x10700, v72
	v_mul_f32_e32 v73, v74, v73
	ds_write_b32 v141, v69
	v_add_f32_e32 v69, v73, v73
	v_cmp_nlt_f32_e32 vcc, s10, v69
	s_and_saveexec_b64 s[0:1], vcc
	s_xor_b64 s[0:1], exec, s[0:1]
	v_mul_f32_e32 v69, 0x3fb8aa3b, v69
	v_exp_f32_e32 v69, v69
	s_nop 0
	v_sub_f32_e32 v72, 1.0, v69
	s_andn2_saveexec_b64 s[0:1], s[0:1]
	v_fmamk_f32 v72, v69, 0x3d2aaaab, v116
	v_fma_f32 v72, v69, v72, 0.5
	v_fma_f32 v72, v69, v72, 1.0
	v_mul_f32_e64 v72, v72, -v69
	s_or_b64 exec, exec, s[0:1]
	v_add_f32_e32 v76, v70, v110
	v_mul_f32_e32 v76, 0xbfb8aa3b, v76
	v_mul_f32_e32 v73, 0x3fb8aa3b, v73
	v_exp_f32_e32 v76, v76
	v_exp_f32_e32 v73, v73
	v_sqrt_f32_e32 v72, v72
	v_or_b32_e32 v69, 2, v136
	v_add_f32_e32 v76, 1.0, v76
	ds_write_b32 v135, v73 offset:8
	ds_read_b32 v73, v135 offset:34312
	v_rcp_f32_e32 v76, v76
	v_add_u32_e32 v77, v69, v100
	s_waitcnt lgkmcnt(0)
	v_mul_f32_e32 v73, v76, v73
	v_mul_f32_e32 v72, v72, v73
	v_lshl_add_u32 v73, v77, 2, 0
	v_add_u32_e32 v142, 0x10700, v73
	ds_write_b32 v142, v72
	v_add_f32_e32 v72, v78, v98
	v_mul_f32_e32 v72, 0xbfb8aa3b, v72
	v_exp_f32_e32 v72, v72
	s_nop 0
	v_add_f32_e32 v72, 1.0, v72
	v_rcp_f32_e32 v72, v72
	s_nop 0
	v_mul_f32_e32 v72, v74, v72
	v_add_f32_e32 v74, v72, v72
	v_cmp_nlt_f32_e32 vcc, s10, v74
	s_and_saveexec_b64 s[0:1], vcc
	s_xor_b64 s[0:1], exec, s[0:1]
	v_mul_f32_e32 v73, 0x3fb8aa3b, v74
	v_exp_f32_e32 v73, v73
	s_nop 0
	v_sub_f32_e32 v73, 1.0, v73
	s_andn2_saveexec_b64 s[0:1], s[0:1]
	v_fmamk_f32 v73, v74, 0x3d2aaaab, v116
	v_fma_f32 v73, v74, v73, 0.5
	v_fma_f32 v73, v74, v73, 1.0
	v_mul_f32_e64 v73, v73, -v74
	s_or_b64 exec, exec, s[0:1]
	v_add_f32_e32 v76, v79, v103
	v_add_f32_e32 v70, v70, v106
	v_mul_f32_e32 v72, 0x3fb8aa3b, v72
	v_mul_f32_e32 v76, 0xbfb8aa3b, v76
	v_mul_f32_e32 v70, 0xbfb8aa3b, v70
	v_exp_f32_e32 v72, v72
	v_exp_f32_e32 v76, v76
	v_exp_f32_e32 v70, v70
	ds_read_b32 v74, v137 offset:34312
	ds_write_b32 v137, v72 offset:8
	v_add_f32_e32 v72, 1.0, v76
	v_add_f32_e32 v70, 1.0, v70
	v_rcp_f32_e32 v72, v72
	v_rcp_f32_e32 v70, v70
	v_sqrt_f32_e32 v73, v73
	v_add_u32_e32 v69, v68, v69
	v_lshl_add_u32 v69, v69, 2, 0
	v_mul_f32_e32 v72, v75, v72
	s_waitcnt lgkmcnt(1)
	v_mul_f32_e32 v70, v70, v74
	v_add_u32_e32 v143, 0x10700, v69
	v_add_f32_e32 v69, v72, v72
	v_mul_f32_e32 v70, v73, v70
	v_cmp_nlt_f32_e32 vcc, s10, v69
	ds_write_b32 v143, v70
	s_and_saveexec_b64 s[0:1], vcc
	s_xor_b64 s[0:1], exec, s[0:1]
	v_mul_f32_e32 v69, 0x3fb8aa3b, v69
	v_exp_f32_e32 v69, v69
	s_nop 0
	v_sub_f32_e32 v70, 1.0, v69
	s_andn2_saveexec_b64 s[0:1], s[0:1]
	v_fmamk_f32 v70, v69, 0x3d2aaaab, v116
	v_fma_f32 v70, v69, v70, 0.5
	v_fma_f32 v70, v69, v70, 1.0
	v_mul_f32_e64 v70, v70, -v69
	s_or_b64 exec, exec, s[0:1]
	v_add_f32_e32 v73, v71, v111
	v_mul_f32_e32 v73, 0xbfb8aa3b, v73
	v_mul_f32_e32 v72, 0x3fb8aa3b, v72
	v_exp_f32_e32 v73, v73
	v_exp_f32_e32 v72, v72
	v_sqrt_f32_e32 v70, v70
	v_or_b32_e32 v69, 3, v136
	v_add_f32_e32 v73, 1.0, v73
	ds_write_b32 v135, v72 offset:12
	ds_read_b32 v72, v135 offset:34316
	v_rcp_f32_e32 v73, v73
	v_add_u32_e32 v74, v69, v100
	s_waitcnt lgkmcnt(0)
	v_mul_f32_e32 v72, v73, v72
	v_mul_f32_e32 v70, v70, v72
	v_lshl_add_u32 v72, v74, 2, 0
	v_add_u32_e32 v111, 0x10700, v72
	ds_write_b32 v111, v70
	v_add_f32_e32 v70, v79, v99
	v_mul_f32_e32 v70, 0xbfb8aa3b, v70
	v_exp_f32_e32 v70, v70
	s_nop 0
	v_add_f32_e32 v70, 1.0, v70
	v_rcp_f32_e32 v70, v70
	s_nop 0
	v_mul_f32_e32 v70, v75, v70
	v_add_f32_e32 v73, v70, v70
	v_cmp_nlt_f32_e32 vcc, s10, v73
	s_and_saveexec_b64 s[0:1], vcc
	s_xor_b64 s[0:1], exec, s[0:1]
	v_mul_f32_e32 v72, 0x3fb8aa3b, v73
	v_exp_f32_e32 v72, v72
	s_nop 0
	v_sub_f32_e32 v72, 1.0, v72
	s_andn2_saveexec_b64 s[0:1], s[0:1]
	v_fmamk_f32 v72, v73, 0x3d2aaaab, v116
	v_fma_f32 v72, v73, v72, 0.5
	v_fma_f32 v72, v73, v72, 1.0
	v_mul_f32_e64 v72, v72, -v73
	s_or_b64 exec, exec, s[0:1]
	v_add_f32_e32 v71, v71, v107
	v_mul_f32_e32 v71, 0xbfb8aa3b, v71
	v_exp_f32_e32 v71, v71
	v_add_f32_e32 v74, v48, v84
	v_mul_f32_e32 v70, 0x3fb8aa3b, v70
	ds_read_b32 v73, v137 offset:34316
	v_add_f32_e32 v71, 1.0, v71
	v_mul_f32_e32 v74, 0xbfb8aa3b, v74
	v_exp_f32_e32 v70, v70
	v_rcp_f32_e32 v71, v71
	v_exp_f32_e32 v74, v74
	v_sqrt_f32_e32 v72, v72
	ds_write_b32 v137, v70 offset:12
	s_waitcnt lgkmcnt(1)
	v_mul_f32_e32 v70, v71, v73
	v_add_f32_e32 v71, 1.0, v74
	v_rcp_f32_e32 v71, v71
	v_add_u32_e32 v69, v68, v69
	v_lshl_add_u32 v69, v69, 2, 0
	v_add_u32_e32 v144, 0x10700, v69
	v_mul_f32_e32 v71, v44, v71
	v_add_f32_e32 v69, v71, v71
	v_mul_f32_e32 v70, v72, v70
	v_cmp_nlt_f32_e32 vcc, s10, v69
	ds_write_b32 v144, v70
	s_and_saveexec_b64 s[0:1], vcc
	s_xor_b64 s[0:1], exec, s[0:1]
	v_mul_f32_e32 v69, 0x3fb8aa3b, v69
	v_exp_f32_e32 v69, v69
	s_nop 0
	v_sub_f32_e32 v70, 1.0, v69
	s_andn2_saveexec_b64 s[0:1], s[0:1]
	v_fmamk_f32 v70, v69, 0x3d2aaaab, v116
	v_fma_f32 v70, v69, v70, 0.5
	v_fma_f32 v70, v69, v70, 1.0
	v_mul_f32_e64 v70, v70, -v69
	s_or_b64 exec, exec, s[0:1]
	v_add_f32_e32 v72, v40, v92
	v_mul_f32_e32 v72, 0xbfb8aa3b, v72
	v_mul_f32_e32 v71, 0x3fb8aa3b, v71
	v_exp_f32_e32 v72, v72
	v_exp_f32_e32 v71, v71
	v_add_f32_e32 v48, v48, v80
	v_mul_f32_e32 v48, 0xbfb8aa3b, v48
	v_exp_f32_e32 v48, v48
	v_add_f32_e32 v72, 1.0, v72
	ds_write_b32 v135, v71 offset:64
	ds_read_b32 v71, v135 offset:34368
	v_rcp_f32_e32 v72, v72
	v_sqrt_f32_e32 v70, v70
	v_add_f32_e32 v48, 1.0, v48
	v_rcp_f32_e32 v48, v48
	v_or_b32_e32 v69, 16, v136
	v_add_u32_e32 v73, v69, v100
	s_waitcnt lgkmcnt(0)
	v_mul_f32_e32 v71, v72, v71
	v_mul_f32_e32 v70, v70, v71
	v_lshl_add_u32 v71, v73, 2, 0
	v_add_u32_e32 v145, 0x10700, v71
	v_mul_f32_e32 v44, v44, v48
	ds_write_b32 v145, v70
	v_add_f32_e32 v70, v44, v44
	v_cmp_nlt_f32_e32 vcc, s10, v70
	s_and_saveexec_b64 s[0:1], vcc
	s_xor_b64 s[0:1], exec, s[0:1]
	v_mul_f32_e32 v48, 0x3fb8aa3b, v70
	v_exp_f32_e32 v48, v48
	s_nop 0
	v_sub_f32_e32 v48, 1.0, v48
	s_andn2_saveexec_b64 s[0:1], s[0:1]
	v_fmamk_f32 v48, v70, 0x3d2aaaab, v116
	v_fma_f32 v48, v70, v48, 0.5
	v_fma_f32 v48, v70, v48, 1.0
	v_mul_f32_e64 v48, v48, -v70
	s_or_b64 exec, exec, s[0:1]
	v_add_f32_e32 v40, v40, v88
	v_mul_f32_e32 v40, 0xbfb8aa3b, v40
	v_exp_f32_e32 v40, v40
	v_add_f32_e32 v71, v49, v85
	v_mul_f32_e32 v44, 0x3fb8aa3b, v44
	v_mul_f32_e32 v71, 0xbfb8aa3b, v71
	v_exp_f32_e32 v44, v44
	v_exp_f32_e32 v71, v71
	v_add_f32_e32 v40, 1.0, v40
	ds_read_b32 v70, v137 offset:34368
	v_rcp_f32_e32 v40, v40
	v_sqrt_f32_e32 v48, v48
	ds_write_b32 v137, v44 offset:64
	v_add_f32_e32 v44, 1.0, v71
	v_rcp_f32_e32 v44, v44
	v_add_u32_e32 v69, v68, v69
	s_waitcnt lgkmcnt(1)
	v_mul_f32_e32 v40, v40, v70
	v_mul_f32_e32 v40, v48, v40
	v_lshl_add_u32 v48, v69, 2, 0
	v_add_u32_e32 v146, 0x10700, v48
	v_mul_f32_e32 v48, v45, v44
	ds_write_b32 v146, v40
	v_add_f32_e32 v40, v48, v48
	v_cmp_nlt_f32_e32 vcc, s10, v40
	s_and_saveexec_b64 s[0:1], vcc
	s_xor_b64 s[0:1], exec, s[0:1]
	v_mul_f32_e32 v40, 0x3fb8aa3b, v40
	v_exp_f32_e32 v40, v40
	s_nop 0
	v_sub_f32_e32 v44, 1.0, v40
	s_andn2_saveexec_b64 s[0:1], s[0:1]
	v_fmamk_f32 v44, v40, 0x3d2aaaab, v116
	v_fma_f32 v44, v40, v44, 0.5
	v_fma_f32 v44, v40, v44, 1.0
	v_mul_f32_e64 v44, v44, -v40
	s_or_b64 exec, exec, s[0:1]
	v_add_f32_e32 v69, v41, v93
	v_mul_f32_e32 v69, 0xbfb8aa3b, v69
	v_mul_f32_e32 v48, 0x3fb8aa3b, v48
	v_exp_f32_e32 v69, v69
	v_exp_f32_e32 v48, v48
	v_sqrt_f32_e32 v44, v44
	v_or_b32_e32 v40, 17, v136
	v_add_f32_e32 v69, 1.0, v69
	ds_write_b32 v135, v48 offset:68
	ds_read_b32 v48, v135 offset:34372
	v_rcp_f32_e32 v69, v69
	v_add_u32_e32 v70, v40, v100
	s_waitcnt lgkmcnt(0)
	v_mul_f32_e32 v48, v69, v48
	v_mul_f32_e32 v44, v44, v48
	v_lshl_add_u32 v48, v70, 2, 0
	v_add_u32_e32 v147, 0x10700, v48
	ds_write_b32 v147, v44
	v_add_f32_e32 v44, v49, v81
	v_mul_f32_e32 v44, 0xbfb8aa3b, v44
	v_exp_f32_e32 v44, v44
	s_nop 0
	v_add_f32_e32 v44, 1.0, v44
	v_rcp_f32_e32 v44, v44
	s_nop 0
	v_mul_f32_e32 v44, v45, v44
	v_add_f32_e32 v48, v44, v44
	v_cmp_nlt_f32_e32 vcc, s10, v48
	s_and_saveexec_b64 s[0:1], vcc
	s_xor_b64 s[0:1], exec, s[0:1]
	v_mul_f32_e32 v45, 0x3fb8aa3b, v48
	v_exp_f32_e32 v45, v45
	s_nop 0
	v_sub_f32_e32 v45, 1.0, v45
	s_andn2_saveexec_b64 s[0:1], s[0:1]
	v_fmamk_f32 v45, v48, 0x3d2aaaab, v116
	v_fma_f32 v45, v48, v45, 0.5
	v_fma_f32 v45, v48, v45, 1.0
	v_mul_f32_e64 v45, v45, -v48
	s_or_b64 exec, exec, s[0:1]
	v_add_f32_e32 v49, v50, v86
	v_add_f32_e32 v41, v41, v89
	v_mul_f32_e32 v44, 0x3fb8aa3b, v44
	v_mul_f32_e32 v49, 0xbfb8aa3b, v49
	v_mul_f32_e32 v41, 0xbfb8aa3b, v41
	v_exp_f32_e32 v44, v44
	v_exp_f32_e32 v49, v49
	v_exp_f32_e32 v41, v41
	ds_read_b32 v48, v137 offset:34372
	ds_write_b32 v137, v44 offset:68
	v_add_f32_e32 v44, 1.0, v49
	v_add_f32_e32 v41, 1.0, v41
	v_rcp_f32_e32 v44, v44
	v_rcp_f32_e32 v41, v41
	v_sqrt_f32_e32 v45, v45
	v_add_u32_e32 v40, v68, v40
	v_lshl_add_u32 v40, v40, 2, 0
	v_mul_f32_e32 v44, v46, v44
	s_waitcnt lgkmcnt(1)
	v_mul_f32_e32 v41, v41, v48
	v_add_u32_e32 v148, 0x10700, v40
	v_add_f32_e32 v40, v44, v44
	v_mul_f32_e32 v41, v45, v41
	v_cmp_nlt_f32_e32 vcc, s10, v40
	ds_write_b32 v148, v41
	s_and_saveexec_b64 s[0:1], vcc
	s_xor_b64 s[0:1], exec, s[0:1]
	v_mul_f32_e32 v40, 0x3fb8aa3b, v40
	v_exp_f32_e32 v40, v40
	s_nop 0
	v_sub_f32_e32 v41, 1.0, v40
	s_andn2_saveexec_b64 s[0:1], s[0:1]
	v_fmamk_f32 v41, v40, 0x3d2aaaab, v116
	v_fma_f32 v41, v40, v41, 0.5
	v_fma_f32 v41, v40, v41, 1.0
	v_mul_f32_e64 v41, v41, -v40
	s_or_b64 exec, exec, s[0:1]
	v_add_f32_e32 v45, v42, v94
	v_mul_f32_e32 v45, 0xbfb8aa3b, v45
	v_mul_f32_e32 v44, 0x3fb8aa3b, v44
	v_exp_f32_e32 v45, v45
	v_exp_f32_e32 v44, v44
	v_sqrt_f32_e32 v41, v41
	v_or_b32_e32 v40, 18, v136
	v_add_f32_e32 v45, 1.0, v45
	ds_write_b32 v135, v44 offset:72
	ds_read_b32 v44, v135 offset:34376
	v_rcp_f32_e32 v45, v45
	v_add_u32_e32 v48, v40, v100
	s_waitcnt lgkmcnt(0)
	v_mul_f32_e32 v44, v45, v44
	v_mul_f32_e32 v41, v41, v44
	v_lshl_add_u32 v44, v48, 2, 0
	v_add_u32_e32 v149, 0x10700, v44
	ds_write_b32 v149, v41
	v_add_f32_e32 v41, v50, v82
	v_mul_f32_e32 v41, 0xbfb8aa3b, v41
	v_exp_f32_e32 v41, v41
	s_nop 0
	v_add_f32_e32 v41, 1.0, v41
	v_rcp_f32_e32 v41, v41
	s_nop 0
	v_mul_f32_e32 v41, v46, v41
	v_add_f32_e32 v45, v41, v41
	v_cmp_nlt_f32_e32 vcc, s10, v45
	s_and_saveexec_b64 s[0:1], vcc
	s_xor_b64 s[0:1], exec, s[0:1]
	v_mul_f32_e32 v44, 0x3fb8aa3b, v45
	v_exp_f32_e32 v44, v44
	s_nop 0
	v_sub_f32_e32 v44, 1.0, v44
	s_andn2_saveexec_b64 s[0:1], s[0:1]
	v_fmamk_f32 v44, v45, 0x3d2aaaab, v116
	v_fma_f32 v44, v45, v44, 0.5
	v_fma_f32 v44, v45, v44, 1.0
	v_mul_f32_e64 v44, v44, -v45
	s_or_b64 exec, exec, s[0:1]
	v_add_f32_e32 v42, v42, v90
	v_mul_f32_e32 v42, 0xbfb8aa3b, v42
	v_exp_f32_e32 v42, v42
	v_add_f32_e32 v46, v51, v87
	v_mul_f32_e32 v41, 0x3fb8aa3b, v41
	ds_read_b32 v45, v137 offset:34376
	v_add_f32_e32 v42, 1.0, v42
	v_mul_f32_e32 v46, 0xbfb8aa3b, v46
	v_exp_f32_e32 v41, v41
	v_rcp_f32_e32 v42, v42
	v_exp_f32_e32 v46, v46
	v_sqrt_f32_e32 v44, v44
	ds_write_b32 v137, v41 offset:72
	s_waitcnt lgkmcnt(1)
	v_mul_f32_e32 v41, v42, v45
	v_add_f32_e32 v42, 1.0, v46
	v_rcp_f32_e32 v42, v42
	v_add_u32_e32 v40, v68, v40
	v_lshl_add_u32 v40, v40, 2, 0
	v_add_u32_e32 v150, 0x10700, v40
	v_mul_f32_e32 v42, v47, v42
	v_add_f32_e32 v40, v42, v42
	v_mul_f32_e32 v41, v44, v41
	v_cmp_nlt_f32_e32 vcc, s10, v40
	ds_write_b32 v150, v41
	s_and_saveexec_b64 s[0:1], vcc
	s_xor_b64 s[0:1], exec, s[0:1]
	v_mul_f32_e32 v40, 0x3fb8aa3b, v40
	v_exp_f32_e32 v40, v40
	s_nop 0
	v_sub_f32_e32 v41, 1.0, v40
	s_andn2_saveexec_b64 s[0:1], s[0:1]
	v_fmamk_f32 v41, v40, 0x3d2aaaab, v116
	v_fma_f32 v41, v40, v41, 0.5
	v_fma_f32 v41, v40, v41, 1.0
	v_mul_f32_e64 v41, v41, -v40
	s_or_b64 exec, exec, s[0:1]
	v_add_f32_e32 v44, v43, v95
	v_mul_f32_e32 v44, 0xbfb8aa3b, v44
	v_mul_f32_e32 v42, 0x3fb8aa3b, v42
	v_exp_f32_e32 v44, v44
	v_exp_f32_e32 v42, v42
	v_sqrt_f32_e32 v41, v41
	v_or_b32_e32 v40, 19, v136
	v_add_f32_e32 v44, 1.0, v44
	ds_write_b32 v135, v42 offset:76
	ds_read_b32 v42, v135 offset:34380
	v_rcp_f32_e32 v44, v44
	v_add_u32_e32 v45, v40, v100
	s_waitcnt lgkmcnt(0)
	v_mul_f32_e32 v42, v44, v42
	v_mul_f32_e32 v41, v41, v42
	v_lshl_add_u32 v42, v45, 2, 0
	v_add_u32_e32 v136, 0x10700, v42
	ds_write_b32 v136, v41
	v_add_f32_e32 v41, v51, v83
	v_mul_f32_e32 v41, 0xbfb8aa3b, v41
	v_exp_f32_e32 v41, v41
	s_nop 0
	v_add_f32_e32 v41, 1.0, v41
	v_rcp_f32_e32 v41, v41
	s_nop 0
	v_mul_f32_e32 v44, v47, v41
	v_add_f32_e32 v41, v44, v44
	v_cmp_nlt_f32_e32 vcc, s10, v41
	s_and_saveexec_b64 s[0:1], vcc
	s_xor_b64 s[0:1], exec, s[0:1]
	v_mul_f32_e32 v41, 0x3fb8aa3b, v41
	v_exp_f32_e32 v41, v41
	s_nop 0
	v_sub_f32_e32 v42, 1.0, v41
	s_andn2_saveexec_b64 s[0:1], s[0:1]
	v_fmamk_f32 v42, v41, 0x3d2aaaab, v116
	v_fma_f32 v42, v41, v42, 0.5
	v_fma_f32 v42, v41, v42, 1.0
	v_mul_f32_e64 v42, v42, -v41
	s_or_b64 exec, exec, s[0:1]
	v_add_f32_e32 v41, v43, v91
	v_mul_f32_e32 v41, 0xbfb8aa3b, v41
	v_exp_f32_e32 v43, v41
	ds_read_b32 v45, v137 offset:34380
	v_mul_f32_e32 v44, 0x3fb8aa3b, v44
	v_sqrt_f32_e32 v42, v42
	v_add_f32_e32 v43, 1.0, v43
	v_rcp_f32_e32 v43, v43
	v_exp_f32_e32 v44, v44
	v_add_u32_e32 v40, v68, v40
	v_lshl_add_u32 v151, v40, 2, s33
	s_waitcnt lgkmcnt(0)
	v_mul_f32_e32 v43, v43, v45
	v_mul_f32_e32 v42, v42, v43
	s_movk_i32 s0, 0x810
	v_lshlrev_b32_e32 v152, 4, v132
	ds_write_b32 v137, v44 offset:76
	ds_write_b32 v151, v42
	v_mul_lo_u32 v40, v132, s0
	s_waitcnt lgkmcnt(0)
	s_barrier
	v_add_u32_e32 v42, v40, v131
	v_lshl_add_u32 v40, v40, 2, v114
	v_or_b32_e32 v153, 1, v152
	v_lshl_add_u32 v42, v42, 2, s33
	ds_read_b32 v154, v40
	ds_read_b32 v157, v42
	v_lshl_add_u32 v40, v153, 7, v153
	v_add_u32_e32 v42, v40, v131
	v_lshl_add_u32 v43, v40, 2, v114
	v_lshl_add_u32 v76, v42, 2, s33
	ds_read2_b32 v[44:45], v43 offset1:129
	ds_read2_b32 v[96:97], v76 offset1:129
	s_waitcnt lgkmcnt(2)
	v_fmac_f32_e32 v157, 0, v154
	v_mov_b32_e32 v41, 1.0
	v_cmp_lt_i32_e64 s[4:5], 0, v132
	s_waitcnt lgkmcnt(1)
	v_mul_f32_e32 v103, v154, v44
	s_waitcnt lgkmcnt(0)
	v_fma_f32 v156, v157, v44, v96
	v_add_u32_e32 v44, 0x400, v43
	ds_read2_b32 v[46:47], v44 offset0:2 offset1:131
	v_add_u32_e32 v44, 0x400, v76
	ds_read2_b32 v[90:91], v44 offset0:2 offset1:131
	v_add_u32_e32 v44, 0x800, v43
	ds_read2_b32 v[48:49], v44 offset0:4 offset1:133
	v_add_u32_e32 v44, 0x800, v76
	ds_read2_b32 v[84:85], v44 offset0:4 offset1:133
	v_add_u32_e32 v44, 0xc00, v43
	ds_read2_b32 v[50:51], v44 offset0:6 offset1:135
	v_add_u32_e32 v44, 0xc00, v76
	v_fmac_f32_e32 v97, v156, v45
	ds_read2_b32 v[72:73], v44 offset0:6 offset1:135
	s_waitcnt lgkmcnt(4)
	v_fma_f32 v155, v97, v46, v90
	v_add_u32_e32 v44, 0x1000, v43
	v_fmac_f32_e32 v91, v155, v47
	ds_read2_b32 v[68:69], v44 offset0:8 offset1:137
	v_add_u32_e32 v44, 0x1000, v76
	s_waitcnt lgkmcnt(3)
	v_fma_f32 v112, v91, v48, v84
	ds_read2_b32 v[70:71], v44 offset0:8 offset1:137
	v_fmac_f32_e32 v85, v112, v49
	s_waitcnt lgkmcnt(2)
	v_fma_f32 v96, v85, v50, v72
	v_fmac_f32_e32 v73, v96, v51
	v_mov_b32_e32 v102, v73
	s_waitcnt lgkmcnt(1)
	v_mov_b32_e32 v44, v68
	v_pk_mul_f32 v[108:109], v[102:103], v[44:45]
	s_waitcnt lgkmcnt(0)
	v_mov_b32_e32 v74, v70
	v_mov_b32_e32 v75, v46
	v_pk_fma_f32 v[78:79], v[102:103], v[44:45], v[74:75]
	v_pk_mul_f32 v[106:107], v[108:109], v[74:75]
	v_mov_b32_e32 v46, v69
	v_mov_b32_e32 v79, v107
	v_pk_mul_f32 v[104:105], v[78:79], v[46:47]
	v_mov_b32_e32 v44, v71
	v_mov_b32_e32 v45, v48
	v_pk_fma_f32 v[70:71], v[78:79], v[46:47], v[44:45]
	v_pk_mul_f32 v[98:99], v[104:105], v[44:45]
	v_add_u32_e32 v44, 0x1400, v43
	ds_read2_b32 v[44:45], v44 offset0:10 offset1:139
	v_add_u32_e32 v46, 0x1400, v76
	ds_read2_b32 v[46:47], v46 offset0:10 offset1:139
	v_add_u32_e32 v48, 0x1800, v43
	ds_read2_b32 v[158:159], v48 offset0:12 offset1:141
	v_add_u32_e32 v48, 0x1800, v76
	v_mov_b32_e32 v71, v99
	ds_read2_b32 v[160:161], v48 offset0:12 offset1:141
	ds_read_b32 v162, v43 offset:7224
	ds_read_b32 v164, v76 offset:7224
	s_waitcnt lgkmcnt(5)
	v_mov_b32_e32 v48, v44
	v_pk_mul_f32 v[100:101], v[70:71], v[48:49]
	s_waitcnt lgkmcnt(4)
	v_mov_b32_e32 v74, v46
	v_mov_b32_e32 v75, v50
	v_pk_fma_f32 v[80:81], v[70:71], v[48:49], v[74:75]
	v_pk_mul_f32 v[94:95], v[100:101], v[74:75]
	v_mov_b32_e32 v50, v45
	v_mov_b32_e32 v81, v95
	v_pk_mul_f32 v[92:93], v[80:81], v[50:51]
	v_mov_b32_e32 v46, v47
	v_mov_b32_e32 v47, v68
	v_pk_fma_f32 v[74:75], v[80:81], v[50:51], v[46:47]
	v_pk_mul_f32 v[88:89], v[92:93], v[46:47]
	s_waitcnt lgkmcnt(3)
	v_mov_b32_e32 v68, v158
	v_mov_b32_e32 v75, v89
	v_pk_mul_f32 v[86:87], v[74:75], v[68:69]
	s_waitcnt lgkmcnt(2)
	v_mov_b32_e32 v46, v160
	v_mov_b32_e32 v47, v44
	v_pk_fma_f32 v[68:69], v[74:75], v[68:69], v[46:47]
	v_pk_mul_f32 v[82:83], v[86:87], v[46:47]
	v_mov_b32_e32 v44, v159
	v_mov_b32_e32 v69, v83
	v_pk_mul_f32 v[76:77], v[68:69], v[44:45]
	v_mov_b32_e32 v46, v161
	v_mov_b32_e32 v47, v158
	v_pk_fma_f32 v[48:49], v[68:69], v[44:45], v[46:47]
	v_pk_mul_f32 v[50:51], v[76:77], v[46:47]
	v_mov_b32_e32 v163, v159
	v_mov_b32_e32 v49, v51
	s_waitcnt lgkmcnt(1)
	v_pk_mul_f32 v[46:47], v[48:49], v[162:163]
	v_mov_b32_e32 v165, v162
	s_waitcnt lgkmcnt(0)
	v_pk_fma_f32 v[158:159], v[48:49], v[162:163], v[164:165]
	v_pk_mul_f32 v[44:45], v[46:47], v[164:165]
	v_add_u32_e32 v43, 0, v134
	v_mov_b32_e32 v44, v158
	v_add_u32_e32 v49, 0x18800, v43
	ds_write_b64 v49, v[44:45]
	s_waitcnt lgkmcnt(0)
	s_barrier
	v_lshlrev_b32_e32 v110, 3, v131
	v_mov_b32_e32 v42, 0
	v_mul_f32_e32 v40, 0, v154
	s_and_saveexec_b64 s[0:1], s[4:5]
	s_cbranch_execz .LBB0_461
	v_cmp_lt_u32_e32 vcc, 7, v132
	v_mov_b32_e32 v46, 0
	v_mov_b32_e32 v41, 1.0
	v_mov_b32_e32 v42, 0
	s_and_saveexec_b64 s[2:3], vcc
	s_cbranch_execz .LBB0_456
	s_add_i32 s6, 0, 0x18800
	v_and_b32_e32 v46, 0x7ffffff8, v132
	v_add_u32_e32 v50, s6, v110
	v_mov_b32_e32 v42, 0
	v_mov_b32_e32 v41, 1.0
	s_mov_b32 s8, 0
	s_mov_b64 s[6:7], 0

.LBB0_1091:
	s_ashr_i32 s12, s96, 3
	s_and_b32 s15, s96, 7
	s_lshl_b32 s14, s12, 6
	s_cmp_lt_i32 s12, 64
	s_movk_i32 s0, 0xff00
	v_readlane_b32 s68, v254, 12
	v_mov_b32_e32 v130, v180
	s_cselect_b32 s0, s0, 0x7ffff800
	s_movk_i32 s1, 0x800
	v_readlane_b32 s74, v254, 18
	v_readlane_b32 s75, v254, 19
	v_readlane_b32 s82, v254, 26
	v_readlane_b32 s83, v254, 27
	s_cselect_b32 s2, 0x100, s1
	s_and_b32 s10, s0, s14
	s_add_i32 s11, s14, -2
	s_lshl_b32 s16, s15, 7
	s_lshl_b32 s0, s15, 8
	s_mov_b64 s[82:83], s[74:75]
	v_lshlrev_b32_e32 v134, 3, v130
	s_add_u32 s0, s82, s0
	v_and_b32_e32 v86, 0x78, v134
	v_add_u32_e32 v85, 0x200, v130
	s_addc_u32 s1, s83, 0
	v_lshlrev_b32_e32 v112, 1, v86
	v_ashrrev_i32_e32 v0, 4, v85
	v_lshl_add_u64 v[62:63], s[0:1], 0, v[112:113]
	s_add_i32 s13, s10, s2
	v_add_u32_e32 v0, s11, v0
	s_movk_i32 s0, 0x230
	v_cmp_gt_i32_e64 s[0:1], s0, v130
	v_cmp_gt_i32_e64 s[4:5], s13, v0
	v_cmp_le_i32_e32 vcc, s10, v0
	s_and_b64 s[2:3], s[0:1], s[4:5]
	v_add_u32_e32 v84, 0x400, v130
	v_mov_b32_e32 v2, s14
	s_and_b64 s[8:9], s[2:3], vcc
	v_ashrrev_i32_e32 v3, 4, v84
	v_cndmask_b32_e64 v0, v2, v0, s[8:9]
	v_add_u32_e32 v3, s11, v3
	v_mad_i64_i32 v[0:1], s[2:3], v0, s97, v[62:63]
	v_cmp_gt_i32_e64 s[6:7], 48, v130
	v_cmp_gt_i32_e64 s[4:5], s13, v3
	v_readlane_b32 s70, v254, 14
	v_readlane_b32 s71, v254, 15
	v_readlane_b32 s76, v254, 20
	v_readlane_b32 s77, v254, 21
	v_readlane_b32 s78, v254, 22
	v_readlane_b32 s79, v254, 23
	v_cmp_le_i32_e32 vcc, s10, v3
	s_and_b64 s[2:3], s[6:7], s[4:5]
	v_readlane_b32 s69, v254, 13
	v_readlane_b32 s72, v254, 16
	v_readlane_b32 s73, v254, 17
	s_mov_b64 s[78:79], s[70:71]
	s_and_b64 s[4:5], s[2:3], vcc
	v_and_b32_e32 v131, 0x7f, v130
	s_mov_b64 s[34:35], s[64:65]
	s_mov_b64 s[76:77], s[68:69]
	v_cndmask_b32_e64 v2, v2, v3, s[4:5]
	v_or_b32_e32 v133, s16, v131
	v_readlane_b32 s60, v254, 44
	v_mad_i64_i32 v[2:3], s[2:3], v2, s97, v[62:63]
	global_load_dwordx4 v[56:59], v[0:1], off
	global_load_dwordx4 v[52:55], v[2:3], off
	v_lshlrev_b32_e32 v0, 2, v133
	v_mov_b32_e32 v1, v113
	v_readlane_b32 s72, v254, 56
	v_readlane_b32 s73, v254, 57
	s_movk_i32 s85, 0x5000
	s_movk_i32 s2, 0x7000
	v_lshl_add_u64 v[2:3], s[72:73], 0, v[0:1]
	v_add_co_u32_e32 v4, vcc, s85, v2
	v_readlane_b32 s74, v254, 58
	s_nop 0
	v_addc_co_u32_e32 v5, vcc, 0, v3, vcc
	v_readlane_b32 s75, v254, 59
	v_add_co_u32_e32 v2, vcc, s2, v2
	s_nop 0
	v_lshl_add_u64 v[0:1], s[74:75], 0, v[0:1]
	v_addc_co_u32_e32 v3, vcc, 0, v3, vcc
	s_movk_i32 s2, 0x1000
	v_ashrrev_i32_e32 v64, 4, v130
	v_add_co_u32_e32 v0, vcc, s2, v0
	s_lshl_b32 s2, s15, 15
	v_lshl_or_b32 v24, v64, 7, v86
	s_add_u32 s2, s78, s2
	s_addc_u32 s3, s79, 0
	v_ashrrev_i32_e32 v25, 31, v24
	v_addc_co_u32_e32 v1, vcc, 0, v1, vcc
	v_lshrrev_b32_e32 v66, 1, v130
	v_lshl_add_u64 v[60:61], v[24:25], 1, s[2:3]
	s_mov_b32 s2, 0x100000
	global_load_dword v82, v[4:5], off offset:-4096
	global_load_dword v83, v[4:5], off
	global_load_dword v80, v[2:3], off offset:-4096
	global_load_dword v67, v[2:3], off
	global_load_dword v81, v[0:1], off
	v_and_b32_e32 v65, 0x60, v66
	v_lshrrev_b32_e32 v0, 2, v130
	v_add_co_u32_e32 v24, vcc, s2, v60
	v_and_or_b32 v136, v0, 12, v65
	s_nop 0
	v_addc_co_u32_e32 v25, vcc, 0, v61, vcc
	v_or_b32_e32 v0, s16, v136
	v_add_co_u32_e32 v28, vcc, 0x102000, v60
	v_lshlrev_b32_e32 v0, 2, v0
	v_readlane_b32 s52, v254, 0
	v_addc_co_u32_e32 v29, vcc, 0, v61, vcc
	v_or_b32_e32 v1, 0x2000, v0
	v_readlane_b32 s53, v254, 1
	v_add_co_u32_e32 v32, vcc, 0x104000, v60
	global_load_dwordx4 v[76:79], v1, s[18:19]
	global_load_dwordx4 v[68:71], v1, s[22:23]
	v_addc_co_u32_e32 v33, vcc, 0, v61, vcc
	s_nop 0
	global_load_dwordx4 v[72:75], v1, s[52:53]
	v_or_b32_e32 v1, 0x2040, v0
	global_load_dwordx4 v[48:51], v1, s[18:19]
	global_load_dwordx4 v[40:43], v1, s[22:23]
	global_load_dwordx4 v[44:47], v1, s[52:53]
	v_or_b32_e32 v1, 0x3000, v0
	v_or_b32_e32 v4, 0x3040, v0
	v_add_co_u32_e32 v36, vcc, 0x106000, v60
	global_load_dwordx4 v[20:23], v1, s[18:19]
	global_load_dwordx4 v[12:15], v1, s[22:23]
	global_load_dwordx4 v[16:19], v1, s[52:53]
	global_load_dwordx4 v[8:11], v4, s[18:19]
	s_nop 0
	global_load_dwordx4 v[0:3], v4, s[22:23]
	s_nop 0
	global_load_dwordx4 v[4:7], v4, s[52:53]
	v_addc_co_u32_e32 v37, vcc, 0, v61, vcc
	global_load_dwordx4 v[24:27], v[24:25], off
	s_nop 0
	global_load_dwordx4 v[28:31], v[28:29], off
	s_nop 0
	global_load_dwordx4 v[32:35], v[32:33], off
	s_nop 0
	global_load_dwordx4 v[36:39], v[36:37], off
	v_add_co_u32_e32 v230, vcc, 0x140000, v60
	s_nop 1
	v_addc_co_u32_e32 v231, vcc, 0, v61, vcc
	global_load_dwordx4 v[182:185], v[230:231], off
	v_add_co_u32_e32 v230, vcc, 0x142000, v60
	s_nop 1
	v_addc_co_u32_e32 v231, vcc, 0, v61, vcc
	global_load_dwordx4 v[186:189], v[230:231], off
	v_add_co_u32_e32 v230, vcc, 0x144000, v60
	s_nop 1
	v_addc_co_u32_e32 v231, vcc, 0, v61, vcc
	global_load_dwordx4 v[190:193], v[230:231], off
	v_add_co_u32_e32 v230, vcc, 0x146000, v60
	s_nop 1
	v_addc_co_u32_e32 v231, vcc, 0, v61, vcc
	global_load_dwordx4 v[194:197], v[230:231], off
	v_add_co_u32_e32 v230, vcc, 0x180000, v60
	s_nop 1
	v_addc_co_u32_e32 v231, vcc, 0, v61, vcc
	global_load_dwordx4 v[198:201], v[230:231], off
	v_add_co_u32_e32 v230, vcc, 0x182000, v60
	s_nop 1
	v_addc_co_u32_e32 v231, vcc, 0, v61, vcc
	global_load_dwordx4 v[202:205], v[230:231], off
	v_add_co_u32_e32 v230, vcc, 0x184000, v60
	s_nop 1
	v_addc_co_u32_e32 v231, vcc, 0, v61, vcc
	global_load_dwordx4 v[206:209], v[230:231], off
	v_add_co_u32_e32 v230, vcc, 0x186000, v60
	s_nop 1
	v_addc_co_u32_e32 v231, vcc, 0, v61, vcc
	global_load_dwordx4 v[210:213], v[230:231], off
	v_add_co_u32_e32 v230, vcc, 0x1c0000, v60
	s_nop 1
	v_addc_co_u32_e32 v231, vcc, 0, v61, vcc
	global_load_dwordx4 v[214:217], v[230:231], off
	v_add_co_u32_e32 v230, vcc, 0x1c2000, v60
	s_nop 1
	v_addc_co_u32_e32 v231, vcc, 0, v61, vcc
	global_load_dwordx4 v[218:221], v[230:231], off
	v_add_co_u32_e32 v230, vcc, 0x1c4000, v60
	s_nop 1
	v_addc_co_u32_e32 v231, vcc, 0, v61, vcc
	global_load_dwordx4 v[222:225], v[230:231], off
	v_add_co_u32_e32 v230, vcc, 0x1c6000, v60
	s_nop 1
	v_addc_co_u32_e32 v231, vcc, 0, v61, vcc
	global_load_dwordx4 v[226:229], v[230:231], off
	s_movk_i32 s2, 0x430
	v_cmp_gt_i32_e32 vcc, s2, v130
	v_lshl_add_u32 v86, v86, 2, 0
	v_readlane_b32 s80, v254, 24
	v_readlane_b32 s81, v254, 25
	v_readlane_b32 s61, v254, 45
	v_readlane_b32 s62, v254, 46
	v_readlane_b32 s63, v254, 47
	v_readlane_b32 s64, v254, 48
	v_readlane_b32 s65, v254, 49
	v_readlane_b32 s66, v254, 50
	v_readlane_b32 s67, v254, 51
	v_readlane_b32 s68, v254, 52
	v_readlane_b32 s69, v254, 53
	v_readlane_b32 s70, v254, 54
	v_readlane_b32 s71, v254, 55
	v_readlane_b32 s54, v254, 2
	v_readlane_b32 s55, v254, 3
	v_readlane_b32 s56, v254, 4
	v_readlane_b32 s57, v254, 5
	v_readlane_b32 s58, v254, 6
	v_readlane_b32 s59, v254, 7
	s_and_saveexec_b64 s[2:3], vcc
	s_cbranch_execz .LBB0_1093
	v_add_u32_e32 v87, s11, v64
	v_cmp_le_i32_e32 vcc, s10, v87
	v_cmp_gt_i32_e64 s[10:11], s13, v87
	v_mov_b32_e32 v88, s14
	s_and_b64 vcc, vcc, s[10:11]
	v_cndmask_b32_e32 v87, v88, v87, vcc
	v_mad_i64_i32 v[62:63], s[10:11], v87, s97, v[62:63]
	global_load_dwordx4 v[88:91], v[62:63], off
	v_and_b32_e32 v62, 0x3fffff80, v134
	v_lshl_add_u32 v63, v62, 2, v86
	v_cndmask_b32_e64 v62, 0, 1.0, vcc
	s_waitcnt vmcnt(0)
	v_lshlrev_b32_e32 v92, 16, v88
	v_and_b32_e32 v93, 0xffff0000, v88
	v_lshlrev_b32_e32 v94, 16, v89
	v_and_b32_e32 v95, 0xffff0000, v89
	v_lshlrev_b32_e32 v96, 16, v90
	v_and_b32_e32 v97, 0xffff0000, v90
	v_lshlrev_b32_e32 v98, 16, v91
	v_and_b32_e32 v99, 0xffff0000, v91
	v_pk_mul_f32 v[88:89], v[62:63], v[92:93] op_sel_hi:[0,1]
	v_pk_mul_f32 v[90:91], v[62:63], v[94:95] op_sel_hi:[0,1]
	v_pk_mul_f32 v[92:93], v[62:63], v[96:97] op_sel_hi:[0,1]
	v_pk_mul_f32 v[94:95], v[62:63], v[98:99] op_sel_hi:[0,1]
	ds_write_b128 v63, v[88:91]
	ds_write_b128 v63, v[92:95] offset:16

.LBB0_1097:
	s_or_b64 exec, exec, s[0:1]
	s_waitcnt vmcnt(0)
	v_lshlrev_b32_e32 v52, 2, v131
	v_lshlrev_b32_e32 v53, 2, v130
	v_add_u32_e32 v114, 0, v52
	v_and_b32_e32 v53, 0xfffffe00, v53
	s_waitcnt lgkmcnt(0)
	s_barrier
	v_add_u32_e32 v55, v114, v53
	v_add3_u32 v53, 0, v53, v52
	ds_read2st64_b32 v[58:59], v53 offset0:2 offset1:4
	ds_read2st64_b32 v[56:57], v55 offset1:8
	v_ashrrev_i32_e32 v132, 7, v130
	s_movk_i32 s0, 0x204
	v_readlane_b32 s2, v253, 18
	s_waitcnt lgkmcnt(0)
	v_mul_f32_e32 v52, v83, v58
	v_fmac_f32_e32 v52, v82, v56
	v_fmac_f32_e32 v52, v80, v59
	ds_read2st64_b32 v[58:59], v53 offset0:6 offset1:10
	s_waitcnt lgkmcnt(0)
	v_mul_f32_e32 v54, v83, v59
	v_fmac_f32_e32 v54, v82, v57
	ds_read2st64_b32 v[56:57], v53 offset0:12 offset1:14
	v_fmac_f32_e32 v52, v67, v58
	v_add_f32_e32 v52, v81, v52
	s_waitcnt lgkmcnt(0)
	v_fmac_f32_e32 v54, v80, v56
	v_fmac_f32_e32 v54, v67, v57
	ds_read2st64_b32 v[56:57], v55 offset0:16 offset1:24
	ds_read2st64_b32 v[58:59], v53 offset0:18 offset1:20
	v_add_f32_e32 v54, v81, v54
	s_waitcnt lgkmcnt(0)
	v_mul_f32_e32 v62, v83, v58
	v_fmac_f32_e32 v62, v82, v56
	v_fmac_f32_e32 v62, v80, v59
	ds_read2st64_b32 v[58:59], v53 offset0:22 offset1:26
	s_waitcnt lgkmcnt(0)
	v_fmac_f32_e32 v62, v67, v58
	v_add_f32_e32 v56, v81, v62
	v_mul_f32_e32 v62, v83, v59
	ds_read2st64_b32 v[58:59], v53 offset0:28 offset1:30
	v_fmac_f32_e32 v62, v82, v57
	s_waitcnt lgkmcnt(0)
	v_fmac_f32_e32 v62, v80, v58
	v_fmac_f32_e32 v62, v67, v59
	v_add_f32_e32 v57, v81, v62
	ds_read2st64_b32 v[58:59], v55 offset0:32 offset1:40
	ds_read2st64_b32 v[62:63], v53 offset0:34 offset1:36
	s_waitcnt lgkmcnt(0)
	v_mul_f32_e32 v84, v83, v62
	v_fmac_f32_e32 v84, v82, v58
	v_fmac_f32_e32 v84, v80, v63
	ds_read2st64_b32 v[62:63], v53 offset0:38 offset1:42
	s_waitcnt lgkmcnt(0)
	v_fmac_f32_e32 v84, v67, v62
	v_add_f32_e32 v58, v81, v84
	v_mul_f32_e32 v84, v83, v63
	ds_read2st64_b32 v[62:63], v53 offset0:44 offset1:46
	v_fmac_f32_e32 v84, v82, v59
	s_waitcnt lgkmcnt(0)
	v_fmac_f32_e32 v84, v80, v62
	v_fmac_f32_e32 v84, v67, v63
	v_add_f32_e32 v59, v81, v84
	ds_read2st64_b32 v[62:63], v55 offset0:48 offset1:56
	ds_read2st64_b32 v[84:85], v53 offset0:50 offset1:52
	s_waitcnt lgkmcnt(0)
	v_mul_f32_e32 v86, v83, v84
	v_fmac_f32_e32 v86, v82, v62
	v_fmac_f32_e32 v86, v80, v85
	ds_read2st64_b32 v[84:85], v53 offset0:54 offset1:58
	s_waitcnt lgkmcnt(0)
	v_fmac_f32_e32 v86, v67, v84
	v_mul_f32_e32 v84, v83, v85
	v_fmac_f32_e32 v84, v82, v63
	ds_read2st64_b32 v[62:63], v53 offset0:60 offset1:62
	v_add_f32_e32 v86, v81, v86
	s_waitcnt lgkmcnt(0)
	v_fmac_f32_e32 v84, v80, v62
	v_fmac_f32_e32 v84, v67, v63
	v_add_f32_e32 v87, v81, v84
	ds_read2st64_b32 v[62:63], v55 offset0:64 offset1:72
	ds_read2st64_b32 v[84:85], v53 offset0:66 offset1:68
	s_waitcnt lgkmcnt(0)
	v_mul_f32_e32 v88, v83, v84
	v_fmac_f32_e32 v88, v82, v62
	v_fmac_f32_e32 v88, v80, v85
	ds_read2st64_b32 v[84:85], v53 offset0:70 offset1:74
	s_waitcnt lgkmcnt(0)
	v_fmac_f32_e32 v88, v67, v84
	v_mul_f32_e32 v84, v83, v85
	v_fmac_f32_e32 v84, v82, v63
	ds_read2st64_b32 v[62:63], v53 offset0:76 offset1:78
	v_add_f32_e32 v88, v81, v88
	s_waitcnt lgkmcnt(0)
	v_fmac_f32_e32 v84, v80, v62
	v_fmac_f32_e32 v84, v67, v63
	v_add_f32_e32 v89, v81, v84
	ds_read2st64_b32 v[62:63], v55 offset0:80 offset1:88
	ds_read2st64_b32 v[84:85], v53 offset0:82 offset1:84
	s_waitcnt lgkmcnt(0)
	v_mul_f32_e32 v90, v83, v84
	v_fmac_f32_e32 v90, v82, v62
	v_fmac_f32_e32 v90, v80, v85
	ds_read2st64_b32 v[84:85], v53 offset0:86 offset1:90
	s_waitcnt lgkmcnt(0)
	v_fmac_f32_e32 v90, v67, v84
	v_mul_f32_e32 v84, v83, v85
	v_fmac_f32_e32 v84, v82, v63
	ds_read2st64_b32 v[62:63], v53 offset0:92 offset1:94
	v_add_f32_e32 v90, v81, v90
	s_waitcnt lgkmcnt(0)
	v_fmac_f32_e32 v84, v80, v62
	v_fmac_f32_e32 v84, v67, v63
	v_add_f32_e32 v91, v81, v84
	ds_read2st64_b32 v[62:63], v55 offset0:96 offset1:104
	ds_read2st64_b32 v[84:85], v53 offset0:98 offset1:100
	s_waitcnt lgkmcnt(0)
	v_mul_f32_e32 v92, v83, v84
	v_fmac_f32_e32 v92, v82, v62
	v_fmac_f32_e32 v92, v80, v85
	ds_read2st64_b32 v[84:85], v53 offset0:102 offset1:106
	s_waitcnt lgkmcnt(0)
	v_fmac_f32_e32 v92, v67, v84
	v_mul_f32_e32 v84, v83, v85
	v_fmac_f32_e32 v84, v82, v63
	ds_read2st64_b32 v[62:63], v53 offset0:108 offset1:110
	v_add_f32_e32 v92, v81, v92
	s_waitcnt lgkmcnt(0)
	v_fmac_f32_e32 v84, v80, v62
	v_fmac_f32_e32 v84, v67, v63
	v_add_f32_e32 v93, v81, v84
	ds_read2st64_b32 v[62:63], v55 offset0:112 offset1:120
	ds_read2st64_b32 v[84:85], v53 offset0:114 offset1:116
	s_waitcnt lgkmcnt(0)
	v_mul_f32_e32 v55, v83, v84
	v_fmac_f32_e32 v55, v82, v62
	v_fmac_f32_e32 v55, v80, v85
	ds_read2st64_b32 v[84:85], v53 offset0:118 offset1:122
	s_waitcnt lgkmcnt(0)
	v_mul_f32_e32 v83, v83, v85
	v_fmac_f32_e32 v83, v82, v63
	ds_read2st64_b32 v[62:63], v53 offset0:124 offset1:126
	v_fmac_f32_e32 v55, v67, v84
	v_add_f32_e32 v55, v81, v55
	s_waitcnt lgkmcnt(0)
	v_fmac_f32_e32 v83, v80, v62
	v_fmac_f32_e32 v83, v67, v63
	v_mad_u64_u32 v[62:63], s[0:1], v132, s0, v[114:115]
	s_movk_i32 s1, 0x110
	v_lshlrev_b32_e32 v67, 1, v131
	v_mul_lo_u32 v63, v132, s1
	ds_write_b32 v62, v52 offset:34304
	v_cvt_pk_bf16_f32 v52, v52, v113
	v_add3_u32 v63, s20, v67, v63
	ds_write_b16 v63, v52
	ds_write_b32 v62, v54 offset:36368
	v_cvt_pk_bf16_f32 v52, v54, v113
	ds_write_b16 v63, v52 offset:1088
	ds_write_b32 v62, v56 offset:38432
	v_cvt_pk_bf16_f32 v52, v56, v113
	ds_write_b16 v63, v52 offset:2176
	ds_write_b32 v62, v57 offset:40496
	v_cvt_pk_bf16_f32 v52, v57, v113
	ds_write_b16 v63, v52 offset:3264
	ds_write_b32 v62, v58 offset:42560
	v_cvt_pk_bf16_f32 v52, v58, v113
	ds_write_b16 v63, v52 offset:4352
	ds_write_b32 v62, v59 offset:44624
	v_cvt_pk_bf16_f32 v52, v59, v113
	ds_write_b16 v63, v52 offset:5440
	ds_write_b32 v62, v86 offset:46688
	v_cvt_pk_bf16_f32 v52, v86, v113
	ds_write_b16 v63, v52 offset:6528
	ds_write_b32 v62, v87 offset:48752
	v_cvt_pk_bf16_f32 v52, v87, v113
	ds_write_b16 v63, v52 offset:7616
	ds_write_b32 v62, v88 offset:50816
	v_cvt_pk_bf16_f32 v52, v88, v113
	ds_write_b16 v63, v52 offset:8704
	ds_write_b32 v62, v89 offset:52880
	v_cvt_pk_bf16_f32 v52, v89, v113
	ds_write_b16 v63, v52 offset:9792
	ds_write_b32 v62, v90 offset:54944
	v_cvt_pk_bf16_f32 v52, v90, v113
	ds_write_b16 v63, v52 offset:10880
	ds_write_b32 v62, v91 offset:57008
	v_cvt_pk_bf16_f32 v52, v91, v113
	ds_write_b16 v63, v52 offset:11968
	ds_write_b32 v62, v92 offset:59072
	v_cvt_pk_bf16_f32 v52, v92, v113
	ds_write_b16 v63, v52 offset:13056
	ds_write_b32 v62, v93 offset:61136
	v_cvt_pk_bf16_f32 v52, v93, v113
	ds_write_b16 v63, v52 offset:14144
	ds_write_b32 v62, v55 offset:63200
	v_cvt_pk_bf16_f32 v52, v55, v113
	v_add_f32_e32 v53, v81, v83
	ds_write_b16 v63, v52 offset:15232
	ds_write_b32 v62, v53 offset:65264
	v_cvt_pk_bf16_f32 v52, v53, v113
	ds_write_b16 v63, v52 offset:16320
	v_mul_lo_u32 v52, v64, s1
	v_add3_u32 v62, s2, v112, v52
	v_ashrrev_i32_e32 v52, 3, v130
	v_and_b32_e32 v53, 15, v130
	s_movk_i32 s0, 0xffe0
	v_and_or_b32 v112, v52, s0, v53
	s_mov_b32 s0, 0x140000
	ds_write_b128 v62, v[24:27]
	ds_write_b128 v62, v[28:31] offset:8704
	ds_write_b128 v62, v[32:35] offset:17408
	ds_write_b128 v62, v[36:39] offset:26112
	v_add_co_u32_e32 v24, vcc, s0, v60
	s_mov_b32 s0, 0x142000
	s_nop 0
	v_addc_co_u32_e32 v25, vcc, 0, v61, vcc
	v_add_co_u32_e32 v28, vcc, s0, v60
	s_mov_b32 s0, 0x144000
	s_nop 0
	v_addc_co_u32_e32 v29, vcc, 0, v61, vcc
	v_add_co_u32_e32 v32, vcc, s0, v60
	s_nop 0
	s_nop 0
	v_addc_co_u32_e32 v33, vcc, 0, v61, vcc
	s_mov_b32 s0, 0x146000
	s_nop 0
	v_and_b32_e32 v52, 24, v66
	s_nop 0
	v_add_co_u32_e32 v32, vcc, s0, v60
	v_lshlrev_b32_e32 v56, 1, v52
	s_nop 0
	v_addc_co_u32_e32 v33, vcc, 0, v61, vcc
	v_or_b32_e32 v57, v65, v53
	s_nop 0
	v_mul_lo_u32 v32, v112, s1
	s_waitcnt lgkmcnt(0)
	s_barrier
	v_add3_u32 v32, s20, v56, v32
	v_mul_u32_u24_e32 v33, 0x110, v57
	v_add3_u32 v33, s2, v56, v33
	ds_read_b128 v[56:59], v32
	ds_read_b128 v[64:67], v33
	ds_read_b128 v[84:87], v32 offset:64
	ds_read_b128 v[88:91], v33 offset:64
	s_waitcnt lgkmcnt(2)
	v_mfma_f32_16x16x32_bf16 v[80:83], v[64:67], v[56:59], 0
	ds_read_b128 v[92:95], v32 offset:128
	ds_read_b128 v[96:99], v33 offset:128
	ds_read_b128 v[104:107], v32 offset:192
	ds_read_b128 v[108:111], v33 offset:192
	ds_read_b128 v[138:141], v33 offset:4416
	s_waitcnt lgkmcnt(5)
	v_mfma_f32_16x16x32_bf16 v[80:83], v[88:91], v[84:87], v[80:83]
	ds_read_b128 v[142:145], v33 offset:4480
	s_mov_b32 s0, 0x180000
	ds_read_b128 v[146:149], v32 offset:4544
	s_waitcnt lgkmcnt(5)
	v_mfma_f32_16x16x32_bf16 v[80:83], v[96:99], v[92:95], v[80:83]
	s_waitcnt lgkmcnt(3)
	v_mfma_f32_16x16x32_bf16 v[100:103], v[108:111], v[104:107], v[80:83]
	s_nop 5
	ds_read_b128 v[80:83], v33 offset:4352
	s_waitcnt lgkmcnt(0)
	v_mfma_f32_16x16x32_bf16 v[56:59], v[80:83], v[56:59], 0
	v_add_f32_e32 v100, v76, v100
	v_mul_f32_e32 v100, 0xbfb8aa3b, v100
	v_exp_f32_e32 v100, v100
	v_mfma_f32_16x16x32_bf16 v[56:59], v[138:141], v[84:87], v[56:59]
	v_add_f32_e32 v100, 1.0, v100
	v_mfma_f32_16x16x32_bf16 v[56:59], v[142:145], v[92:95], v[56:59]
	ds_read_b128 v[92:95], v33 offset:4544
	v_rcp_f32_e32 v100, v100
	s_waitcnt lgkmcnt(0)
	v_mfma_f32_16x16x32_bf16 v[84:87], v[92:95], v[104:107], v[56:59]
	s_nop 3
	ds_read_b128 v[56:59], v32 offset:4352
	ds_read_b128 v[104:107], v32 offset:4416
	v_mul_f32_e32 v100, v72, v100
	s_waitcnt lgkmcnt(1)
	v_mfma_f32_16x16x32_bf16 v[64:67], v[64:67], v[56:59], 0
	v_add_f32_e32 v135, v100, v100
	s_waitcnt lgkmcnt(0)
	v_mfma_f32_16x16x32_bf16 v[64:67], v[88:91], v[104:107], v[64:67]
	ds_read_b128 v[88:91], v32 offset:4480
	s_waitcnt lgkmcnt(0)
	s_barrier
	s_nop 0
	ds_write_b128 v62, v[182:185]
	s_nop 0
	ds_write_b128 v62, v[186:189] offset:8704
	s_nop 0
	ds_write_b128 v62, v[190:193] offset:17408
	s_nop 0
	ds_write_b128 v62, v[194:197] offset:26112
	v_add_co_u32_e32 v24, vcc, s0, v60
	s_mov_b32 s0, 0x182000
	s_nop 0
	v_addc_co_u32_e32 v25, vcc, 0, v61, vcc
	v_add_co_u32_e32 v28, vcc, s0, v60
	s_mov_b32 s0, 0x184000
	s_nop 0
	v_addc_co_u32_e32 v29, vcc, 0, v61, vcc
	v_add_co_u32_e32 v34, vcc, s0, v60
	s_nop 0
	s_nop 0
	v_addc_co_u32_e32 v35, vcc, 0, v61, vcc
	s_mov_b32 s0, 0x186000
	s_nop 0
	v_add_co_u32_e32 v38, vcc, s0, v60
	s_nop 0
	s_nop 0
	v_addc_co_u32_e32 v39, vcc, 0, v61, vcc
	s_nop 0
	v_mfma_f32_16x16x32_bf16 v[56:59], v[80:83], v[56:59], 0
	s_waitcnt lgkmcnt(0)
	s_barrier
	s_mov_b32 s0, 0x1c0000
	v_mfma_f32_16x16x32_bf16 v[56:59], v[138:141], v[104:107], v[56:59]
	s_waitcnt lgkmcnt(4)
	v_mfma_f32_16x16x32_bf16 v[64:67], v[96:99], v[88:91], v[64:67]
	v_mfma_f32_16x16x32_bf16 v[56:59], v[142:145], v[88:91], v[56:59]
	v_mfma_f32_16x16x32_bf16 v[96:99], v[108:111], v[146:149], v[64:67]
	v_mfma_f32_16x16x32_bf16 v[80:83], v[92:95], v[146:149], v[56:59]
	s_nop 5
	ds_read_b128 v[56:59], v32
	ds_read_b128 v[64:67], v33
	ds_read_b128 v[92:95], v32 offset:64
	ds_read_b128 v[104:107], v33 offset:64
	ds_read_b128 v[138:141], v32 offset:128
	ds_read_b128 v[142:145], v33 offset:128
	s_waitcnt lgkmcnt(4)
	v_mfma_f32_16x16x32_bf16 v[88:91], v[64:67], v[56:59], 0
	ds_read_b128 v[146:149], v32 offset:192
	ds_read_b128 v[150:153], v33 offset:192
	ds_read_b128 v[154:157], v33 offset:4416
	ds_read_b128 v[158:161], v33 offset:4480
	s_waitcnt lgkmcnt(6)
	v_mfma_f32_16x16x32_bf16 v[88:91], v[104:107], v[92:95], v[88:91]
	ds_read_b128 v[162:165], v32 offset:4480
	s_waitcnt lgkmcnt(5)
	v_mfma_f32_16x16x32_bf16 v[88:91], v[142:145], v[138:141], v[88:91]
	s_waitcnt lgkmcnt(3)
	v_mfma_f32_16x16x32_bf16 v[108:111], v[150:153], v[146:149], v[88:91]
	s_nop 5
	ds_read_b128 v[88:91], v33 offset:4352
	s_waitcnt lgkmcnt(0)
	v_mfma_f32_16x16x32_bf16 v[56:59], v[88:91], v[56:59], 0
	v_mfma_f32_16x16x32_bf16 v[56:59], v[154:157], v[92:95], v[56:59]
	v_mfma_f32_16x16x32_bf16 v[56:59], v[158:161], v[138:141], v[56:59]
	ds_read_b128 v[138:141], v33 offset:4544
	s_waitcnt lgkmcnt(0)
	v_mfma_f32_16x16x32_bf16 v[92:95], v[138:141], v[146:149], v[56:59]
	s_nop 4
	ds_read_b128 v[56:59], v32 offset:4352
	ds_read_b128 v[146:149], v32 offset:4416
	s_waitcnt lgkmcnt(1)
	v_mfma_f32_16x16x32_bf16 v[64:67], v[64:67], v[56:59], 0
	v_mfma_f32_16x16x32_bf16 v[56:59], v[88:91], v[56:59], 0
	s_waitcnt lgkmcnt(0)
	v_mfma_f32_16x16x32_bf16 v[64:67], v[104:107], v[146:149], v[64:67]
	v_mfma_f32_16x16x32_bf16 v[56:59], v[154:157], v[146:149], v[56:59]
	v_mfma_f32_16x16x32_bf16 v[64:67], v[142:145], v[162:165], v[64:67]
	ds_read_b128 v[142:145], v32 offset:4544
	s_waitcnt lgkmcnt(0)
	s_barrier
	s_nop 0
	ds_write_b128 v62, v[198:201]
	s_nop 0
	ds_write_b128 v62, v[202:205] offset:8704
	s_nop 0
	ds_write_b128 v62, v[206:209] offset:17408
	s_nop 0
	ds_write_b128 v62, v[210:213] offset:26112
	v_add_co_u32_e32 v24, vcc, s0, v60
	s_mov_b32 s0, 0x1c2000
	s_nop 0
	v_addc_co_u32_e32 v25, vcc, 0, v61, vcc
	v_mfma_f32_16x16x32_bf16 v[56:59], v[158:161], v[162:165], v[56:59]
	s_nop 0
	v_add_co_u32_e32 v24, vcc, s0, v60
	s_mov_b32 s0, 0x1c4000
	s_nop 0
	v_addc_co_u32_e32 v25, vcc, 0, v61, vcc
	s_waitcnt lgkmcnt(4)
	v_mfma_f32_16x16x32_bf16 v[104:107], v[150:153], v[142:145], v[64:67]
	s_nop 2
	s_nop 0
	v_add_co_u32_e32 v24, vcc, s0, v60
	s_mov_b32 s0, 0x1c6000
	s_nop 0
	v_addc_co_u32_e32 v25, vcc, 0, v61, vcc
	v_mfma_f32_16x16x32_bf16 v[88:91], v[138:141], v[142:145], v[56:59]
	s_nop 0
	v_add_co_u32_e32 v24, vcc, s0, v60
	s_nop 1
	v_addc_co_u32_e32 v25, vcc, 0, v61, vcc
	s_nop 0
	s_waitcnt lgkmcnt(0)
	s_barrier
	ds_read_b128 v[24:27], v32
	ds_read_b128 v[56:59], v33
	ds_read_b128 v[146:149], v32 offset:64
	ds_read_b128 v[150:153], v33 offset:64
	ds_read_b128 v[154:157], v32 offset:128
	ds_read_b128 v[158:161], v33 offset:128
	ds_read_b128 v[162:165], v32 offset:192
	ds_read_b128 v[166:169], v33 offset:192
	ds_read_b128 v[170:173], v33 offset:4352
	ds_read_b128 v[174:177], v33 offset:4416
	s_waitcnt lgkmcnt(8)
	v_mfma_f32_16x16x32_bf16 v[28:31], v[56:59], v[24:27], 0
	v_cmp_nlt_f32_e32 vcc, s21, v135
	s_waitcnt lgkmcnt(1)
	v_mfma_f32_16x16x32_bf16 v[24:27], v[170:173], v[24:27], 0
	v_mfma_f32_16x16x32_bf16 v[28:31], v[150:153], v[146:149], v[28:31]
	s_waitcnt lgkmcnt(0)
	v_mfma_f32_16x16x32_bf16 v[24:27], v[174:177], v[146:149], v[24:27]
	ds_read_b128 v[146:149], v33 offset:4480
	v_mfma_f32_16x16x32_bf16 v[28:31], v[158:161], v[154:157], v[28:31]
	s_waitcnt lgkmcnt(0)
	v_mfma_f32_16x16x32_bf16 v[24:27], v[146:149], v[154:157], v[24:27]
	ds_read_b128 v[154:157], v33 offset:4544
	v_mfma_f32_16x16x32_bf16 v[52:55], v[166:169], v[162:165], v[28:31]
	s_waitcnt lgkmcnt(0)
	v_mfma_f32_16x16x32_bf16 v[28:31], v[154:157], v[162:165], v[24:27]
	ds_read_b128 v[162:165], v32 offset:4416
	s_nop 2
	ds_read_b128 v[24:27], v32 offset:4352
	s_waitcnt lgkmcnt(0)
	v_mfma_f32_16x16x32_bf16 v[56:59], v[56:59], v[24:27], 0
	v_mfma_f32_16x16x32_bf16 v[24:27], v[170:173], v[24:27], 0
	v_mfma_f32_16x16x32_bf16 v[56:59], v[150:153], v[162:165], v[56:59]
	ds_read_b128 v[150:153], v32 offset:4480
	v_mfma_f32_16x16x32_bf16 v[24:27], v[174:177], v[162:165], v[24:27]
	s_waitcnt lgkmcnt(0)
	v_mfma_f32_16x16x32_bf16 v[56:59], v[158:161], v[150:153], v[56:59]
	ds_read_b128 v[158:161], v32 offset:4544
	s_waitcnt lgkmcnt(0)
	s_barrier
	s_nop 0
	ds_write_b128 v62, v[214:217]
	s_nop 0
	ds_write_b128 v62, v[218:221] offset:8704
	s_nop 0
	ds_write_b128 v62, v[222:225] offset:17408
	s_nop 0
	ds_write_b128 v62, v[226:229] offset:26112
	v_mfma_f32_16x16x32_bf16 v[24:27], v[146:149], v[150:153], v[24:27]
	s_waitcnt lgkmcnt(0)
	s_barrier
	ds_read_b128 v[34:37], v32
	ds_read_b128 v[64:67], v33
	ds_read_b128 v[138:141], v32 offset:64
	ds_read_b128 v[142:145], v33 offset:64
	s_waitcnt lgkmcnt(8)
	v_mfma_f32_16x16x32_bf16 v[56:59], v[166:169], v[158:161], v[56:59]
	ds_read_b128 v[146:149], v32 offset:128
	ds_read_b128 v[150:153], v33 offset:128
	v_mfma_f32_16x16x32_bf16 v[24:27], v[154:157], v[158:161], v[24:27]
	ds_read_b128 v[154:157], v32 offset:192
	ds_read_b128 v[158:161], v33 offset:192
	ds_read_b128 v[162:165], v33 offset:4352
	ds_read_b128 v[166:169], v33 offset:4416
	s_waitcnt lgkmcnt(8)
	v_mfma_f32_16x16x32_bf16 v[60:63], v[64:67], v[34:37], 0
	ds_read_b128 v[170:173], v32 offset:4416
	s_waitcnt lgkmcnt(2)
	v_mfma_f32_16x16x32_bf16 v[34:37], v[162:165], v[34:37], 0
	v_mfma_f32_16x16x32_bf16 v[60:63], v[142:145], v[138:141], v[60:63]
	s_waitcnt lgkmcnt(1)
	v_mfma_f32_16x16x32_bf16 v[34:37], v[166:169], v[138:141], v[34:37]
	ds_read_b128 v[138:141], v33 offset:4480
	v_mfma_f32_16x16x32_bf16 v[60:63], v[150:153], v[146:149], v[60:63]
	s_waitcnt lgkmcnt(0)
	v_mfma_f32_16x16x32_bf16 v[34:37], v[138:141], v[146:149], v[34:37]
	ds_read_b128 v[146:149], v33 offset:4544
	v_mfma_f32_16x16x32_bf16 v[60:63], v[158:161], v[154:157], v[60:63]
	s_waitcnt lgkmcnt(0)
	v_mfma_f32_16x16x32_bf16 v[36:39], v[146:149], v[154:157], v[34:37]
	ds_read_b128 v[154:157], v32 offset:4352
	s_waitcnt lgkmcnt(0)
	v_mfma_f32_16x16x32_bf16 v[64:67], v[64:67], v[154:157], 0
	v_mfma_f32_16x16x32_bf16 v[64:67], v[142:145], v[170:173], v[64:67]
	ds_read_b128 v[142:145], v32 offset:4480
	ds_read_b128 v[32:35], v32 offset:4544
	s_waitcnt lgkmcnt(0)
	s_barrier
	s_waitcnt lgkmcnt(1)
	v_mfma_f32_16x16x32_bf16 v[64:67], v[150:153], v[142:145], v[64:67]
	v_mfma_f32_16x16x32_bf16 v[150:153], v[162:165], v[154:157], 0
	v_mfma_f32_16x16x32_bf16 v[150:153], v[166:169], v[170:173], v[150:153]
	v_mfma_f32_16x16x32_bf16 v[138:141], v[138:141], v[142:145], v[150:153]
	s_waitcnt lgkmcnt(0)
	v_mfma_f32_16x16x32_bf16 v[64:67], v[158:161], v[32:35], v[64:67]
	v_mfma_f32_16x16x32_bf16 v[32:35], v[146:149], v[32:35], v[138:141]
	s_and_saveexec_b64 s[0:1], vcc
	s_xor_b64 s[0:1], exec, s[0:1]
	v_mul_f32_e32 v135, 0x3fb8aa3b, v135
	v_exp_f32_e32 v135, v135
	s_nop 0
	v_sub_f32_e32 v137, 1.0, v135
	s_andn2_saveexec_b64 s[0:1], s[0:1]
	v_fmamk_f32 v137, v135, 0x3d2aaaab, v116
	v_fma_f32 v137, v135, v137, 0.5
	v_fma_f32 v137, v135, v137, 1.0
	v_mul_f32_e64 v137, v137, -v135
	s_or_b64 exec, exec, s[0:1]
	v_add_f32_e32 v76, v76, v96
	v_add_f32_e32 v108, v68, v108
	v_mul_f32_e32 v76, 0xbfb8aa3b, v76
	v_mul_f32_e32 v108, 0xbfb8aa3b, v108
	v_exp_f32_e32 v76, v76
	v_exp_f32_e32 v108, v108
	v_mul_f32_e32 v100, 0x3fb8aa3b, v100
	v_exp_f32_e32 v138, v100
	v_lshl_add_u32 v100, v112, 7, v112
	v_add_u32_e32 v112, v100, v136
	v_lshl_add_u32 v135, v112, 2, 0
	v_add_f32_e32 v76, 1.0, v76
	v_add_f32_e32 v108, 1.0, v108
	v_sqrt_f32_e32 v112, v137
	ds_read_b32 v137, v135 offset:34304
	v_rcp_f32_e32 v76, v76
	v_rcp_f32_e32 v108, v108
	ds_write_b32 v135, v138
	v_add_u32_e32 v138, 0x10700, v135
	v_mul_f32_e32 v76, v72, v76
	s_waitcnt lgkmcnt(1)
	v_mul_f32_e32 v108, v108, v137
	v_add_f32_e32 v96, v76, v76
	v_mul_f32_e32 v108, v112, v108
	v_cmp_nlt_f32_e32 vcc, s21, v96
	ds_write_b32 v138, v108
	s_and_saveexec_b64 s[0:1], vcc
	s_xor_b64 s[0:1], exec, s[0:1]
	v_mul_f32_e32 v72, 0x3fb8aa3b, v96
	v_exp_f32_e32 v72, v72
	s_nop 0
	v_sub_f32_e32 v72, 1.0, v72
	s_andn2_saveexec_b64 s[0:1], s[0:1]
	v_fmamk_f32 v72, v96, 0x3d2aaaab, v116
	v_fma_f32 v72, v96, v72, 0.5
	v_fma_f32 v72, v96, v72, 1.0
	v_mul_f32_e64 v72, v72, -v96
	s_or_b64 exec, exec, s[0:1]
	v_add_f32_e32 v68, v68, v104
	v_mul_f32_e32 v68, 0xbfb8aa3b, v68
	v_exp_f32_e32 v68, v68
	v_sqrt_f32_e32 v72, v72
	v_add_f32_e32 v68, 1.0, v68
	v_rcp_f32_e32 v96, v68
	v_mul_f32_e32 v68, 0x3fb8aa3b, v76
	v_exp_f32_e32 v76, v68
	v_add_u32_e32 v68, 0x810, v100
	v_add_u32_e32 v104, v68, v136
	v_lshl_add_u32 v137, v104, 2, 0
	ds_write_b32 v137, v76
	ds_read_b32 v76, v137 offset:34304
	v_add_u32_e32 v139, 0x10700, v137
	s_waitcnt lgkmcnt(0)
	v_mul_f32_e32 v76, v96, v76
	v_mul_f32_e32 v72, v72, v76
	ds_write_b32 v139, v72
	v_add_f32_e32 v72, v77, v101
	v_mul_f32_e32 v72, 0xbfb8aa3b, v72
	v_exp_f32_e32 v72, v72
	s_nop 0
	v_add_f32_e32 v72, 1.0, v72
	v_rcp_f32_e32 v72, v72
	s_nop 0
	v_mul_f32_e32 v96, v73, v72
	v_add_f32_e32 v72, v96, v96
	v_cmp_nlt_f32_e32 vcc, s21, v72
	s_and_saveexec_b64 s[0:1], vcc
	s_xor_b64 s[0:1], exec, s[0:1]
	v_mul_f32_e32 v72, 0x3fb8aa3b, v72
	v_exp_f32_e32 v72, v72
	s_nop 0
	v_sub_f32_e32 v76, 1.0, v72
	s_andn2_saveexec_b64 s[0:1], s[0:1]
	v_fmamk_f32 v76, v72, 0x3d2aaaab, v116
	v_fma_f32 v76, v72, v76, 0.5
	v_fma_f32 v76, v72, v76, 1.0
	v_mul_f32_e64 v76, v76, -v72
	s_or_b64 exec, exec, s[0:1]
	v_add_f32_e32 v101, v69, v109
	v_mul_f32_e32 v101, 0xbfb8aa3b, v101
	v_mul_f32_e32 v96, 0x3fb8aa3b, v96
	v_exp_f32_e32 v101, v101
	v_exp_f32_e32 v96, v96
	v_sqrt_f32_e32 v76, v76
	v_or_b32_e32 v72, 1, v136
	v_add_f32_e32 v101, 1.0, v101
	ds_write_b32 v135, v96 offset:4
	ds_read_b32 v96, v135 offset:34308
	v_rcp_f32_e32 v101, v101
	v_add_u32_e32 v104, v72, v100
	s_waitcnt lgkmcnt(0)
	v_mul_f32_e32 v96, v101, v96
	v_mul_f32_e32 v76, v76, v96
	v_lshl_add_u32 v96, v104, 2, 0
	v_add_u32_e32 v140, 0x10700, v96
	ds_write_b32 v140, v76
	v_add_f32_e32 v76, v77, v97
	v_mul_f32_e32 v76, 0xbfb8aa3b, v76
	v_exp_f32_e32 v76, v76
	s_nop 0
	v_add_f32_e32 v76, 1.0, v76
	v_rcp_f32_e32 v76, v76
	s_nop 0
	v_mul_f32_e32 v73, v73, v76
	v_add_f32_e32 v77, v73, v73
	v_cmp_nlt_f32_e32 vcc, s21, v77
	s_and_saveexec_b64 s[0:1], vcc
	s_xor_b64 s[0:1], exec, s[0:1]
	v_mul_f32_e32 v76, 0x3fb8aa3b, v77
	v_exp_f32_e32 v76, v76
	s_nop 0
	v_sub_f32_e32 v76, 1.0, v76
	s_andn2_saveexec_b64 s[0:1], s[0:1]
	v_fmamk_f32 v76, v77, 0x3d2aaaab, v116
	v_fma_f32 v76, v77, v76, 0.5
	v_fma_f32 v76, v77, v76, 1.0
	v_mul_f32_e64 v76, v76, -v77
	s_or_b64 exec, exec, s[0:1]
	v_add_f32_e32 v69, v69, v105
	v_mul_f32_e32 v69, 0xbfb8aa3b, v69
	v_add_f32_e32 v96, v78, v102
	v_exp_f32_e32 v69, v69
	v_mul_f32_e32 v73, 0x3fb8aa3b, v73
	v_mul_f32_e32 v96, 0xbfb8aa3b, v96
	v_exp_f32_e32 v73, v73
	v_exp_f32_e32 v96, v96
	v_add_f32_e32 v69, 1.0, v69
	ds_read_b32 v77, v137 offset:34308
	v_rcp_f32_e32 v69, v69
	ds_write_b32 v137, v73 offset:4
	v_add_f32_e32 v73, 1.0, v96
	v_sqrt_f32_e32 v76, v76
	v_rcp_f32_e32 v73, v73
	v_add_u32_e32 v72, v68, v72
	s_waitcnt lgkmcnt(1)
	v_mul_f32_e32 v69, v69, v77
	v_lshl_add_u32 v72, v72, 2, 0
	v_mul_f32_e32 v69, v76, v69
	v_add_u32_e32 v141, 0x10700, v72
	v_mul_f32_e32 v73, v74, v73
	ds_write_b32 v141, v69
	v_add_f32_e32 v69, v73, v73
	v_cmp_nlt_f32_e32 vcc, s21, v69
	s_and_saveexec_b64 s[0:1], vcc
	s_xor_b64 s[0:1], exec, s[0:1]
	v_mul_f32_e32 v69, 0x3fb8aa3b, v69
	v_exp_f32_e32 v69, v69
	s_nop 0
	v_sub_f32_e32 v72, 1.0, v69
	s_andn2_saveexec_b64 s[0:1], s[0:1]
	v_fmamk_f32 v72, v69, 0x3d2aaaab, v116
	v_fma_f32 v72, v69, v72, 0.5
	v_fma_f32 v72, v69, v72, 1.0
	v_mul_f32_e64 v72, v72, -v69
	s_or_b64 exec, exec, s[0:1]
	v_add_f32_e32 v76, v70, v110
	v_mul_f32_e32 v76, 0xbfb8aa3b, v76
	v_mul_f32_e32 v73, 0x3fb8aa3b, v73
	v_exp_f32_e32 v76, v76
	v_exp_f32_e32 v73, v73
	v_sqrt_f32_e32 v72, v72
	v_or_b32_e32 v69, 2, v136
	v_add_f32_e32 v76, 1.0, v76
	ds_write_b32 v135, v73 offset:8
	ds_read_b32 v73, v135 offset:34312
	v_rcp_f32_e32 v76, v76
	v_add_u32_e32 v77, v69, v100
	s_waitcnt lgkmcnt(0)
	v_mul_f32_e32 v73, v76, v73
	v_mul_f32_e32 v72, v72, v73
	v_lshl_add_u32 v73, v77, 2, 0
	v_add_u32_e32 v142, 0x10700, v73
	ds_write_b32 v142, v72
	v_add_f32_e32 v72, v78, v98
	v_mul_f32_e32 v72, 0xbfb8aa3b, v72
	v_exp_f32_e32 v72, v72
	s_nop 0
	v_add_f32_e32 v72, 1.0, v72
	v_rcp_f32_e32 v72, v72
	s_nop 0
	v_mul_f32_e32 v72, v74, v72
	v_add_f32_e32 v74, v72, v72
	v_cmp_nlt_f32_e32 vcc, s21, v74
	s_and_saveexec_b64 s[0:1], vcc
	s_xor_b64 s[0:1], exec, s[0:1]
	v_mul_f32_e32 v73, 0x3fb8aa3b, v74
	v_exp_f32_e32 v73, v73
	s_nop 0
	v_sub_f32_e32 v73, 1.0, v73
	s_andn2_saveexec_b64 s[0:1], s[0:1]
	v_fmamk_f32 v73, v74, 0x3d2aaaab, v116
	v_fma_f32 v73, v74, v73, 0.5
	v_fma_f32 v73, v74, v73, 1.0
	v_mul_f32_e64 v73, v73, -v74
	s_or_b64 exec, exec, s[0:1]
	v_add_f32_e32 v76, v79, v103
	v_add_f32_e32 v70, v70, v106
	v_mul_f32_e32 v72, 0x3fb8aa3b, v72
	v_mul_f32_e32 v76, 0xbfb8aa3b, v76
	v_mul_f32_e32 v70, 0xbfb8aa3b, v70
	v_exp_f32_e32 v72, v72
	v_exp_f32_e32 v76, v76
	v_exp_f32_e32 v70, v70
	ds_read_b32 v74, v137 offset:34312
	ds_write_b32 v137, v72 offset:8
	v_add_f32_e32 v72, 1.0, v76
	v_add_f32_e32 v70, 1.0, v70
	v_rcp_f32_e32 v72, v72
	v_rcp_f32_e32 v70, v70
	v_sqrt_f32_e32 v73, v73
	v_add_u32_e32 v69, v68, v69
	v_lshl_add_u32 v69, v69, 2, 0
	v_mul_f32_e32 v72, v75, v72
	s_waitcnt lgkmcnt(1)
	v_mul_f32_e32 v70, v70, v74
	v_add_u32_e32 v143, 0x10700, v69
	v_add_f32_e32 v69, v72, v72
	v_mul_f32_e32 v70, v73, v70
	v_cmp_nlt_f32_e32 vcc, s21, v69
	ds_write_b32 v143, v70
	s_and_saveexec_b64 s[0:1], vcc
	s_xor_b64 s[0:1], exec, s[0:1]
	v_mul_f32_e32 v69, 0x3fb8aa3b, v69
	v_exp_f32_e32 v69, v69
	s_nop 0
	v_sub_f32_e32 v70, 1.0, v69
	s_andn2_saveexec_b64 s[0:1], s[0:1]
	v_fmamk_f32 v70, v69, 0x3d2aaaab, v116
	v_fma_f32 v70, v69, v70, 0.5
	v_fma_f32 v70, v69, v70, 1.0
	v_mul_f32_e64 v70, v70, -v69
	s_or_b64 exec, exec, s[0:1]
	v_add_f32_e32 v73, v71, v111
	v_mul_f32_e32 v73, 0xbfb8aa3b, v73
	v_mul_f32_e32 v72, 0x3fb8aa3b, v72
	v_exp_f32_e32 v73, v73
	v_exp_f32_e32 v72, v72
	v_sqrt_f32_e32 v70, v70
	v_or_b32_e32 v69, 3, v136
	v_add_f32_e32 v73, 1.0, v73
	ds_write_b32 v135, v72 offset:12
	ds_read_b32 v72, v135 offset:34316
	v_rcp_f32_e32 v73, v73
	v_add_u32_e32 v74, v69, v100
	s_waitcnt lgkmcnt(0)
	v_mul_f32_e32 v72, v73, v72
	v_mul_f32_e32 v70, v70, v72
	v_lshl_add_u32 v72, v74, 2, 0
	v_add_u32_e32 v111, 0x10700, v72
	ds_write_b32 v111, v70
	v_add_f32_e32 v70, v79, v99
	v_mul_f32_e32 v70, 0xbfb8aa3b, v70
	v_exp_f32_e32 v70, v70
	s_nop 0
	v_add_f32_e32 v70, 1.0, v70
	v_rcp_f32_e32 v70, v70
	s_nop 0
	v_mul_f32_e32 v70, v75, v70
	v_add_f32_e32 v73, v70, v70
	v_cmp_nlt_f32_e32 vcc, s21, v73
	s_and_saveexec_b64 s[0:1], vcc
	s_xor_b64 s[0:1], exec, s[0:1]
	v_mul_f32_e32 v72, 0x3fb8aa3b, v73
	v_exp_f32_e32 v72, v72
	s_nop 0
	v_sub_f32_e32 v72, 1.0, v72
	s_andn2_saveexec_b64 s[0:1], s[0:1]
	v_fmamk_f32 v72, v73, 0x3d2aaaab, v116
	v_fma_f32 v72, v73, v72, 0.5
	v_fma_f32 v72, v73, v72, 1.0
	v_mul_f32_e64 v72, v72, -v73
	s_or_b64 exec, exec, s[0:1]
	v_add_f32_e32 v71, v71, v107
	v_mul_f32_e32 v71, 0xbfb8aa3b, v71
	v_exp_f32_e32 v71, v71
	v_add_f32_e32 v74, v48, v84
	v_mul_f32_e32 v70, 0x3fb8aa3b, v70
	ds_read_b32 v73, v137 offset:34316
	v_add_f32_e32 v71, 1.0, v71
	v_mul_f32_e32 v74, 0xbfb8aa3b, v74
	v_exp_f32_e32 v70, v70
	v_rcp_f32_e32 v71, v71
	v_exp_f32_e32 v74, v74
	v_sqrt_f32_e32 v72, v72
	ds_write_b32 v137, v70 offset:12
	s_waitcnt lgkmcnt(1)
	v_mul_f32_e32 v70, v71, v73
	v_add_f32_e32 v71, 1.0, v74
	v_rcp_f32_e32 v71, v71
	v_add_u32_e32 v69, v68, v69
	v_lshl_add_u32 v69, v69, 2, 0
	v_add_u32_e32 v144, 0x10700, v69
	v_mul_f32_e32 v71, v44, v71
	v_add_f32_e32 v69, v71, v71
	v_mul_f32_e32 v70, v72, v70
	v_cmp_nlt_f32_e32 vcc, s21, v69
	ds_write_b32 v144, v70
	s_and_saveexec_b64 s[0:1], vcc
	s_xor_b64 s[0:1], exec, s[0:1]
	v_mul_f32_e32 v69, 0x3fb8aa3b, v69
	v_exp_f32_e32 v69, v69
	s_nop 0
	v_sub_f32_e32 v70, 1.0, v69
	s_andn2_saveexec_b64 s[0:1], s[0:1]
	v_fmamk_f32 v70, v69, 0x3d2aaaab, v116
	v_fma_f32 v70, v69, v70, 0.5
	v_fma_f32 v70, v69, v70, 1.0
	v_mul_f32_e64 v70, v70, -v69
	s_or_b64 exec, exec, s[0:1]
	v_add_f32_e32 v72, v40, v92
	v_mul_f32_e32 v72, 0xbfb8aa3b, v72
	v_mul_f32_e32 v71, 0x3fb8aa3b, v71
	v_exp_f32_e32 v72, v72
	v_exp_f32_e32 v71, v71
	v_add_f32_e32 v48, v48, v80
	v_mul_f32_e32 v48, 0xbfb8aa3b, v48
	v_exp_f32_e32 v48, v48
	v_add_f32_e32 v72, 1.0, v72
	ds_write_b32 v135, v71 offset:64
	ds_read_b32 v71, v135 offset:34368
	v_rcp_f32_e32 v72, v72
	v_sqrt_f32_e32 v70, v70
	v_add_f32_e32 v48, 1.0, v48
	v_rcp_f32_e32 v48, v48
	v_or_b32_e32 v69, 16, v136
	v_add_u32_e32 v73, v69, v100
	s_waitcnt lgkmcnt(0)
	v_mul_f32_e32 v71, v72, v71
	v_mul_f32_e32 v70, v70, v71
	v_lshl_add_u32 v71, v73, 2, 0
	v_add_u32_e32 v145, 0x10700, v71
	v_mul_f32_e32 v44, v44, v48
	ds_write_b32 v145, v70
	v_add_f32_e32 v70, v44, v44
	v_cmp_nlt_f32_e32 vcc, s21, v70
	s_and_saveexec_b64 s[0:1], vcc
	s_xor_b64 s[0:1], exec, s[0:1]
	v_mul_f32_e32 v48, 0x3fb8aa3b, v70
	v_exp_f32_e32 v48, v48
	s_nop 0
	v_sub_f32_e32 v48, 1.0, v48
	s_andn2_saveexec_b64 s[0:1], s[0:1]
	v_fmamk_f32 v48, v70, 0x3d2aaaab, v116
	v_fma_f32 v48, v70, v48, 0.5
	v_fma_f32 v48, v70, v48, 1.0
	v_mul_f32_e64 v48, v48, -v70
	s_or_b64 exec, exec, s[0:1]
	v_add_f32_e32 v40, v40, v88
	v_mul_f32_e32 v40, 0xbfb8aa3b, v40
	v_exp_f32_e32 v40, v40
	v_add_f32_e32 v71, v49, v85
	v_mul_f32_e32 v44, 0x3fb8aa3b, v44
	v_mul_f32_e32 v71, 0xbfb8aa3b, v71
	v_exp_f32_e32 v44, v44
	v_exp_f32_e32 v71, v71
	v_add_f32_e32 v40, 1.0, v40
	ds_read_b32 v70, v137 offset:34368
	v_rcp_f32_e32 v40, v40
	v_sqrt_f32_e32 v48, v48
	ds_write_b32 v137, v44 offset:64
	v_add_f32_e32 v44, 1.0, v71
	v_rcp_f32_e32 v44, v44
	v_add_u32_e32 v69, v68, v69
	s_waitcnt lgkmcnt(1)
	v_mul_f32_e32 v40, v40, v70
	v_mul_f32_e32 v40, v48, v40
	v_lshl_add_u32 v48, v69, 2, 0
	v_add_u32_e32 v146, 0x10700, v48
	v_mul_f32_e32 v48, v45, v44
	ds_write_b32 v146, v40
	v_add_f32_e32 v40, v48, v48
	v_cmp_nlt_f32_e32 vcc, s21, v40
	s_and_saveexec_b64 s[0:1], vcc
	s_xor_b64 s[0:1], exec, s[0:1]
	v_mul_f32_e32 v40, 0x3fb8aa3b, v40
	v_exp_f32_e32 v40, v40
	s_nop 0
	v_sub_f32_e32 v44, 1.0, v40
	s_andn2_saveexec_b64 s[0:1], s[0:1]
	v_fmamk_f32 v44, v40, 0x3d2aaaab, v116
	v_fma_f32 v44, v40, v44, 0.5
	v_fma_f32 v44, v40, v44, 1.0
	v_mul_f32_e64 v44, v44, -v40
	s_or_b64 exec, exec, s[0:1]
	v_add_f32_e32 v69, v41, v93
	v_mul_f32_e32 v69, 0xbfb8aa3b, v69
	v_mul_f32_e32 v48, 0x3fb8aa3b, v48
	v_exp_f32_e32 v69, v69
	v_exp_f32_e32 v48, v48
	v_sqrt_f32_e32 v44, v44
	v_or_b32_e32 v40, 17, v136
	v_add_f32_e32 v69, 1.0, v69
	ds_write_b32 v135, v48 offset:68
	ds_read_b32 v48, v135 offset:34372
	v_rcp_f32_e32 v69, v69
	v_add_u32_e32 v70, v40, v100
	s_waitcnt lgkmcnt(0)
	v_mul_f32_e32 v48, v69, v48
	v_mul_f32_e32 v44, v44, v48
	v_lshl_add_u32 v48, v70, 2, 0
	v_add_u32_e32 v147, 0x10700, v48
	ds_write_b32 v147, v44
	v_add_f32_e32 v44, v49, v81
	v_mul_f32_e32 v44, 0xbfb8aa3b, v44
	v_exp_f32_e32 v44, v44
	s_nop 0
	v_add_f32_e32 v44, 1.0, v44
	v_rcp_f32_e32 v44, v44
	s_nop 0
	v_mul_f32_e32 v44, v45, v44
	v_add_f32_e32 v48, v44, v44
	v_cmp_nlt_f32_e32 vcc, s21, v48
	s_and_saveexec_b64 s[0:1], vcc
	s_xor_b64 s[0:1], exec, s[0:1]
	v_mul_f32_e32 v45, 0x3fb8aa3b, v48
	v_exp_f32_e32 v45, v45
	s_nop 0
	v_sub_f32_e32 v45, 1.0, v45
	s_andn2_saveexec_b64 s[0:1], s[0:1]
	v_fmamk_f32 v45, v48, 0x3d2aaaab, v116
	v_fma_f32 v45, v48, v45, 0.5
	v_fma_f32 v45, v48, v45, 1.0
	v_mul_f32_e64 v45, v45, -v48
	s_or_b64 exec, exec, s[0:1]
	v_add_f32_e32 v49, v50, v86
	v_add_f32_e32 v41, v41, v89
	v_mul_f32_e32 v44, 0x3fb8aa3b, v44
	v_mul_f32_e32 v49, 0xbfb8aa3b, v49
	v_mul_f32_e32 v41, 0xbfb8aa3b, v41
	v_exp_f32_e32 v44, v44
	v_exp_f32_e32 v49, v49
	v_exp_f32_e32 v41, v41
	ds_read_b32 v48, v137 offset:34372
	ds_write_b32 v137, v44 offset:68
	v_add_f32_e32 v44, 1.0, v49
	v_add_f32_e32 v41, 1.0, v41
	v_rcp_f32_e32 v44, v44
	v_rcp_f32_e32 v41, v41
	v_sqrt_f32_e32 v45, v45
	v_add_u32_e32 v40, v68, v40
	v_lshl_add_u32 v40, v40, 2, 0
	v_mul_f32_e32 v44, v46, v44
	s_waitcnt lgkmcnt(1)
	v_mul_f32_e32 v41, v41, v48
	v_add_u32_e32 v148, 0x10700, v40
	v_add_f32_e32 v40, v44, v44
	v_mul_f32_e32 v41, v45, v41
	v_cmp_nlt_f32_e32 vcc, s21, v40
	ds_write_b32 v148, v41
	s_and_saveexec_b64 s[0:1], vcc
	s_xor_b64 s[0:1], exec, s[0:1]
	v_mul_f32_e32 v40, 0x3fb8aa3b, v40
	v_exp_f32_e32 v40, v40
	s_nop 0
	v_sub_f32_e32 v41, 1.0, v40
	s_andn2_saveexec_b64 s[0:1], s[0:1]
	v_fmamk_f32 v41, v40, 0x3d2aaaab, v116
	v_fma_f32 v41, v40, v41, 0.5
	v_fma_f32 v41, v40, v41, 1.0
	v_mul_f32_e64 v41, v41, -v40
	s_or_b64 exec, exec, s[0:1]
	v_add_f32_e32 v45, v42, v94
	v_mul_f32_e32 v45, 0xbfb8aa3b, v45
	v_mul_f32_e32 v44, 0x3fb8aa3b, v44
	v_exp_f32_e32 v45, v45
	v_exp_f32_e32 v44, v44
	v_sqrt_f32_e32 v41, v41
	v_or_b32_e32 v40, 18, v136
	v_add_f32_e32 v45, 1.0, v45
	ds_write_b32 v135, v44 offset:72
	ds_read_b32 v44, v135 offset:34376
	v_rcp_f32_e32 v45, v45
	v_add_u32_e32 v48, v40, v100
	s_waitcnt lgkmcnt(0)
	v_mul_f32_e32 v44, v45, v44
	v_mul_f32_e32 v41, v41, v44
	v_lshl_add_u32 v44, v48, 2, 0
	v_add_u32_e32 v149, 0x10700, v44
	ds_write_b32 v149, v41
	v_add_f32_e32 v41, v50, v82
	v_mul_f32_e32 v41, 0xbfb8aa3b, v41
	v_exp_f32_e32 v41, v41
	s_nop 0
	v_add_f32_e32 v41, 1.0, v41
	v_rcp_f32_e32 v41, v41
	s_nop 0
	v_mul_f32_e32 v41, v46, v41
	v_add_f32_e32 v45, v41, v41
	v_cmp_nlt_f32_e32 vcc, s21, v45
	s_and_saveexec_b64 s[0:1], vcc
	s_xor_b64 s[0:1], exec, s[0:1]
	v_mul_f32_e32 v44, 0x3fb8aa3b, v45
	v_exp_f32_e32 v44, v44
	s_nop 0
	v_sub_f32_e32 v44, 1.0, v44
	s_andn2_saveexec_b64 s[0:1], s[0:1]
	v_fmamk_f32 v44, v45, 0x3d2aaaab, v116
	v_fma_f32 v44, v45, v44, 0.5
	v_fma_f32 v44, v45, v44, 1.0
	v_mul_f32_e64 v44, v44, -v45
	s_or_b64 exec, exec, s[0:1]
	v_add_f32_e32 v42, v42, v90
	v_mul_f32_e32 v42, 0xbfb8aa3b, v42
	v_exp_f32_e32 v42, v42
	v_add_f32_e32 v46, v51, v87
	v_mul_f32_e32 v41, 0x3fb8aa3b, v41
	ds_read_b32 v45, v137 offset:34376
	v_add_f32_e32 v42, 1.0, v42
	v_mul_f32_e32 v46, 0xbfb8aa3b, v46
	v_exp_f32_e32 v41, v41
	v_rcp_f32_e32 v42, v42
	v_exp_f32_e32 v46, v46
	v_sqrt_f32_e32 v44, v44
	ds_write_b32 v137, v41 offset:72
	s_waitcnt lgkmcnt(1)
	v_mul_f32_e32 v41, v42, v45
	v_add_f32_e32 v42, 1.0, v46
	v_rcp_f32_e32 v42, v42
	v_add_u32_e32 v40, v68, v40
	v_lshl_add_u32 v40, v40, 2, 0
	v_add_u32_e32 v150, 0x10700, v40
	v_mul_f32_e32 v42, v47, v42
	v_add_f32_e32 v40, v42, v42
	v_mul_f32_e32 v41, v44, v41
	v_cmp_nlt_f32_e32 vcc, s21, v40
	ds_write_b32 v150, v41
	s_and_saveexec_b64 s[0:1], vcc
	s_xor_b64 s[0:1], exec, s[0:1]
	v_mul_f32_e32 v40, 0x3fb8aa3b, v40
	v_exp_f32_e32 v40, v40
	s_nop 0
	v_sub_f32_e32 v41, 1.0, v40
	s_andn2_saveexec_b64 s[0:1], s[0:1]
	v_fmamk_f32 v41, v40, 0x3d2aaaab, v116
	v_fma_f32 v41, v40, v41, 0.5
	v_fma_f32 v41, v40, v41, 1.0
	v_mul_f32_e64 v41, v41, -v40
	s_or_b64 exec, exec, s[0:1]
	v_add_f32_e32 v44, v43, v95
	v_mul_f32_e32 v44, 0xbfb8aa3b, v44
	v_mul_f32_e32 v42, 0x3fb8aa3b, v42
	v_exp_f32_e32 v44, v44
	v_exp_f32_e32 v42, v42
	v_sqrt_f32_e32 v41, v41
	v_or_b32_e32 v40, 19, v136
	v_add_f32_e32 v44, 1.0, v44
	ds_write_b32 v135, v42 offset:76
	ds_read_b32 v42, v135 offset:34380
	v_rcp_f32_e32 v44, v44
	v_add_u32_e32 v45, v40, v100
	s_waitcnt lgkmcnt(0)
	v_mul_f32_e32 v42, v44, v42
	v_mul_f32_e32 v41, v41, v42
	v_lshl_add_u32 v42, v45, 2, 0
	v_add_u32_e32 v136, 0x10700, v42
	ds_write_b32 v136, v41
	v_add_f32_e32 v41, v51, v83
	v_mul_f32_e32 v41, 0xbfb8aa3b, v41
	v_exp_f32_e32 v41, v41
	s_nop 0
	v_add_f32_e32 v41, 1.0, v41
	v_rcp_f32_e32 v41, v41
	s_nop 0
	v_mul_f32_e32 v44, v47, v41
	v_add_f32_e32 v41, v44, v44
	v_cmp_nlt_f32_e32 vcc, s21, v41
	s_and_saveexec_b64 s[0:1], vcc
	s_xor_b64 s[0:1], exec, s[0:1]
	v_mul_f32_e32 v41, 0x3fb8aa3b, v41
	v_exp_f32_e32 v41, v41
	s_nop 0
	v_sub_f32_e32 v42, 1.0, v41
	s_andn2_saveexec_b64 s[0:1], s[0:1]
	v_fmamk_f32 v42, v41, 0x3d2aaaab, v116
	v_fma_f32 v42, v41, v42, 0.5
	v_fma_f32 v42, v41, v42, 1.0
	v_mul_f32_e64 v42, v42, -v41
	s_or_b64 exec, exec, s[0:1]
	v_add_f32_e32 v41, v43, v91
	v_mul_f32_e32 v41, 0xbfb8aa3b, v41
	v_exp_f32_e32 v43, v41
	ds_read_b32 v45, v137 offset:34380
	v_mul_f32_e32 v44, 0x3fb8aa3b, v44
	v_sqrt_f32_e32 v42, v42
	v_add_f32_e32 v43, 1.0, v43
	v_rcp_f32_e32 v43, v43
	v_exp_f32_e32 v44, v44
	v_add_u32_e32 v40, v68, v40
	v_lshl_add_u32 v151, v40, 2, s20
	s_waitcnt lgkmcnt(0)
	v_mul_f32_e32 v43, v43, v45
	v_mul_f32_e32 v42, v42, v43
	s_movk_i32 s0, 0x810
	v_lshlrev_b32_e32 v152, 4, v132
	ds_write_b32 v137, v44 offset:76
	ds_write_b32 v151, v42
	v_mul_lo_u32 v40, v132, s0
	s_waitcnt lgkmcnt(0)
	s_barrier
	v_add_u32_e32 v42, v40, v131
	v_lshl_add_u32 v40, v40, 2, v114
	v_or_b32_e32 v153, 1, v152
	v_lshl_add_u32 v42, v42, 2, s20
	ds_read_b32 v154, v40
	ds_read_b32 v157, v42
	v_lshl_add_u32 v40, v153, 7, v153
	v_add_u32_e32 v42, v40, v131
	v_lshl_add_u32 v43, v40, 2, v114
	v_lshl_add_u32 v76, v42, 2, s20
	ds_read2_b32 v[44:45], v43 offset1:129
	ds_read2_b32 v[96:97], v76 offset1:129
	s_waitcnt lgkmcnt(2)
	v_fmac_f32_e32 v157, 0, v154
	v_mov_b32_e32 v41, 1.0
	v_cmp_lt_i32_e64 s[4:5], 0, v132
	s_waitcnt lgkmcnt(1)
	v_mul_f32_e32 v103, v154, v44
	s_waitcnt lgkmcnt(0)
	v_fma_f32 v156, v157, v44, v96
	v_add_u32_e32 v44, 0x400, v43
	ds_read2_b32 v[46:47], v44 offset0:2 offset1:131
	v_add_u32_e32 v44, 0x400, v76
	ds_read2_b32 v[90:91], v44 offset0:2 offset1:131
	v_add_u32_e32 v44, 0x800, v43
	ds_read2_b32 v[48:49], v44 offset0:4 offset1:133
	v_add_u32_e32 v44, 0x800, v76
	ds_read2_b32 v[84:85], v44 offset0:4 offset1:133
	v_add_u32_e32 v44, 0xc00, v43
	ds_read2_b32 v[50:51], v44 offset0:6 offset1:135
	v_add_u32_e32 v44, 0xc00, v76
	v_fmac_f32_e32 v97, v156, v45
	ds_read2_b32 v[72:73], v44 offset0:6 offset1:135
	s_waitcnt lgkmcnt(4)
	v_fma_f32 v155, v97, v46, v90
	v_add_u32_e32 v44, 0x1000, v43
	v_fmac_f32_e32 v91, v155, v47
	ds_read2_b32 v[68:69], v44 offset0:8 offset1:137
	v_add_u32_e32 v44, 0x1000, v76
	s_waitcnt lgkmcnt(3)
	v_fma_f32 v112, v91, v48, v84
	ds_read2_b32 v[70:71], v44 offset0:8 offset1:137
	v_fmac_f32_e32 v85, v112, v49
	s_waitcnt lgkmcnt(2)
	v_fma_f32 v96, v85, v50, v72
	v_fmac_f32_e32 v73, v96, v51
	v_mov_b32_e32 v102, v73
	s_waitcnt lgkmcnt(1)
	v_mov_b32_e32 v44, v68
	v_pk_mul_f32 v[108:109], v[102:103], v[44:45]
	s_waitcnt lgkmcnt(0)
	v_mov_b32_e32 v74, v70
	v_mov_b32_e32 v75, v46
	v_pk_fma_f32 v[78:79], v[102:103], v[44:45], v[74:75]
	v_pk_mul_f32 v[106:107], v[108:109], v[74:75]
	v_mov_b32_e32 v46, v69
	v_mov_b32_e32 v79, v107
	v_pk_mul_f32 v[104:105], v[78:79], v[46:47]
	v_mov_b32_e32 v44, v71
	v_mov_b32_e32 v45, v48
	v_pk_fma_f32 v[70:71], v[78:79], v[46:47], v[44:45]
	v_pk_mul_f32 v[98:99], v[104:105], v[44:45]
	v_add_u32_e32 v44, 0x1400, v43
	ds_read2_b32 v[44:45], v44 offset0:10 offset1:139
	v_add_u32_e32 v46, 0x1400, v76
	ds_read2_b32 v[46:47], v46 offset0:10 offset1:139
	v_add_u32_e32 v48, 0x1800, v43
	ds_read2_b32 v[158:159], v48 offset0:12 offset1:141
	v_add_u32_e32 v48, 0x1800, v76
	v_mov_b32_e32 v71, v99
	ds_read2_b32 v[160:161], v48 offset0:12 offset1:141
	ds_read_b32 v162, v43 offset:7224
	ds_read_b32 v164, v76 offset:7224
	s_waitcnt lgkmcnt(5)
	v_mov_b32_e32 v48, v44
	v_pk_mul_f32 v[100:101], v[70:71], v[48:49]
	s_waitcnt lgkmcnt(4)
	v_mov_b32_e32 v74, v46
	v_mov_b32_e32 v75, v50
	v_pk_fma_f32 v[80:81], v[70:71], v[48:49], v[74:75]
	v_pk_mul_f32 v[94:95], v[100:101], v[74:75]
	v_mov_b32_e32 v50, v45
	v_mov_b32_e32 v81, v95
	v_pk_mul_f32 v[92:93], v[80:81], v[50:51]
	v_mov_b32_e32 v46, v47
	v_mov_b32_e32 v47, v68
	v_pk_fma_f32 v[74:75], v[80:81], v[50:51], v[46:47]
	v_pk_mul_f32 v[88:89], v[92:93], v[46:47]
	s_waitcnt lgkmcnt(3)
	v_mov_b32_e32 v68, v158
	v_mov_b32_e32 v75, v89
	v_pk_mul_f32 v[86:87], v[74:75], v[68:69]
	s_waitcnt lgkmcnt(2)
	v_mov_b32_e32 v46, v160
	v_mov_b32_e32 v47, v44
	v_pk_fma_f32 v[68:69], v[74:75], v[68:69], v[46:47]
	v_pk_mul_f32 v[82:83], v[86:87], v[46:47]
	v_mov_b32_e32 v44, v159
	v_mov_b32_e32 v69, v83
	v_pk_mul_f32 v[76:77], v[68:69], v[44:45]
	v_mov_b32_e32 v46, v161
	v_mov_b32_e32 v47, v158
	v_pk_fma_f32 v[48:49], v[68:69], v[44:45], v[46:47]
	v_pk_mul_f32 v[50:51], v[76:77], v[46:47]
	v_mov_b32_e32 v163, v159
	v_mov_b32_e32 v49, v51
	s_waitcnt lgkmcnt(1)
	v_pk_mul_f32 v[46:47], v[48:49], v[162:163]
	v_mov_b32_e32 v165, v162
	s_waitcnt lgkmcnt(0)
	v_pk_fma_f32 v[158:159], v[48:49], v[162:163], v[164:165]
	v_pk_mul_f32 v[44:45], v[46:47], v[164:165]
	v_add_u32_e32 v43, 0, v134
	v_mov_b32_e32 v44, v158
	v_add_u32_e32 v49, 0x18800, v43
	ds_write_b64 v49, v[44:45]
	s_waitcnt lgkmcnt(0)
	s_barrier
	v_lshlrev_b32_e32 v110, 3, v131
	v_mov_b32_e32 v42, 0
	v_mul_f32_e32 v40, 0, v154
	s_and_saveexec_b64 s[0:1], s[4:5]
	s_cbranch_execz .LBB0_1171
	v_cmp_lt_u32_e32 vcc, 7, v132
	v_mov_b32_e32 v46, 0
	v_mov_b32_e32 v41, 1.0
	v_mov_b32_e32 v42, 0
	s_and_saveexec_b64 s[2:3], vcc
	s_cbranch_execz .LBB0_1166
	s_add_i32 s6, 0, 0x18800
	v_and_b32_e32 v46, 0x7ffffff8, v132
	v_add_u32_e32 v50, s6, v110
	v_mov_b32_e32 v42, 0
	v_mov_b32_e32 v41, 1.0
	s_mov_b32 s8, 0
	s_mov_b64 s[6:7], 0
